# FFN1-down and out_proj residual epilogues: all 16 residual-row loads hoisted to the top of the tile epilogue (before the un-stagger barrier), counted vmcnt per round instead of vmcnt(0) drains
# speedup vs baseline: 1.0483x; 1.0047x over previous
.Lg248_noy:
.LBB0_248:
	ds_read_b128 v[144:147], v151
	ds_read_b128 v[156:159], v151 offset:1024
	ds_read_b128 v[160:163], v151 offset:2048
	ds_read_b128 v[164:167], v151 offset:3072
	s_add_u32 s26, s20, 0x100
	s_addc_u32 s27, s21, 0
	s_cmp_eq_u32 s59, 40
	s_cselect_b32 s31, s9, s27
	s_cselect_b32 s30, s8, s26
	s_cselect_b32 s29, s11, s58
	s_cselect_b32 s28, s10, s57
	s_add_i32 m0, s41, 0xc000
	ds_read_b128 v[168:171], v152
	ds_read_b128 v[172:175], v152 offset:1024
	ds_read_b128 v[176:179], v152 offset:2048
	ds_read_b128 v[180:183], v152 offset:3072
	ds_read_b128 v[184:187], v152 offset:4096
	ds_read_b128 v[188:191], v152 offset:5120
	ds_read_b128 v[192:195], v152 offset:6144
	ds_read_b128 v[196:199], v152 offset:7168
	global_load_lds_dwordx4 v136, s[20:21]
	s_add_i32 m0, s41, 0xe000
	s_nop 0
	global_load_lds_dwordx4 v138, s[20:21]
	s_waitcnt lgkmcnt(8)
	s_barrier
	s_waitcnt lgkmcnt(0)
	s_setprio 1
	s_waitcnt lgkmcnt(0)
	v_mfma_f32_16x16x32_bf16 v[124:127], v[144:147], v[168:171], v[124:127]
	v_mfma_f32_16x16x32_bf16 v[120:123], v[160:163], v[168:171], v[120:123]
	v_mfma_f32_16x16x32_bf16 v[108:111], v[144:147], v[176:179], v[108:111]
	v_mfma_f32_16x16x32_bf16 v[104:107], v[160:163], v[176:179], v[104:107]
	v_mfma_f32_16x16x32_bf16 v[92:95], v[144:147], v[184:187], v[92:95]
	v_mfma_f32_16x16x32_bf16 v[88:91], v[160:163], v[184:187], v[88:91]
	v_mfma_f32_16x16x32_bf16 v[76:79], v[144:147], v[192:195], v[76:79]
	v_mfma_f32_16x16x32_bf16 v[72:75], v[160:163], v[192:195], v[72:75]
	v_mfma_f32_16x16x32_bf16 v[124:127], v[156:159], v[172:175], v[124:127]
	v_mfma_f32_16x16x32_bf16 v[120:123], v[164:167], v[172:175], v[120:123]
	v_mfma_f32_16x16x32_bf16 v[108:111], v[156:159], v[180:183], v[108:111]
	v_mfma_f32_16x16x32_bf16 v[104:107], v[164:167], v[180:183], v[104:107]
	v_mfma_f32_16x16x32_bf16 v[92:95], v[156:159], v[188:191], v[92:95]
	v_mfma_f32_16x16x32_bf16 v[88:91], v[164:167], v[188:191], v[88:91]
	v_mfma_f32_16x16x32_bf16 v[76:79], v[156:159], v[196:199], v[76:79]
	v_mfma_f32_16x16x32_bf16 v[72:75], v[164:167], v[196:199], v[72:75]
	s_setprio 0
	s_barrier
	s_add_i32 s20, s51, s40
	s_add_u32 s80, s28, 0x80
	s_addc_u32 s81, s29, 0
	s_mov_b32 m0, s20
	ds_read_b128 v[200:203], v153
	ds_read_b128 v[204:207], v153 offset:1024
	ds_read_b128 v[208:211], v153 offset:2048
	ds_read_b128 v[212:215], v153 offset:3072
	global_load_lds_dwordx4 v130, s[28:29]
	s_add_i32 m0, s20, 0x2000
	s_nop 0
	global_load_lds_dwordx4 v134, s[28:29]
	s_barrier
	s_waitcnt lgkmcnt(0)
	s_setprio 1
	s_waitcnt lgkmcnt(0)
	v_mfma_f32_16x16x32_bf16 v[116:119], v[200:203], v[168:171], v[116:119]
	v_mfma_f32_16x16x32_bf16 v[112:115], v[208:211], v[168:171], v[112:115]
	v_mfma_f32_16x16x32_bf16 v[100:103], v[200:203], v[176:179], v[100:103]
	v_mfma_f32_16x16x32_bf16 v[96:99], v[208:211], v[176:179], v[96:99]
	v_mfma_f32_16x16x32_bf16 v[84:87], v[200:203], v[184:187], v[84:87]
	v_mfma_f32_16x16x32_bf16 v[80:83], v[208:211], v[184:187], v[80:83]
	v_mfma_f32_16x16x32_bf16 v[68:71], v[200:203], v[192:195], v[68:71]
	v_mfma_f32_16x16x32_bf16 v[64:67], v[208:211], v[192:195], v[64:67]
	v_mfma_f32_16x16x32_bf16 v[116:119], v[204:207], v[172:175], v[116:119]
	v_mfma_f32_16x16x32_bf16 v[112:115], v[212:215], v[172:175], v[112:115]
	v_mfma_f32_16x16x32_bf16 v[100:103], v[204:207], v[180:183], v[100:103]
	v_mfma_f32_16x16x32_bf16 v[96:99], v[212:215], v[180:183], v[96:99]
	v_mfma_f32_16x16x32_bf16 v[84:87], v[204:207], v[188:191], v[84:87]
	v_mfma_f32_16x16x32_bf16 v[80:83], v[212:215], v[188:191], v[80:83]
	v_mfma_f32_16x16x32_bf16 v[68:71], v[204:207], v[196:199], v[68:71]
	v_mfma_f32_16x16x32_bf16 v[64:67], v[212:215], v[196:199], v[64:67]
	s_setprio 0
	s_mov_b32 m0, s41
	s_add_u32 s82, s30, 0x80
	s_addc_u32 s83, s31, 0
	s_barrier
	ds_read_b128 v[168:171], v152 offset:16384
	ds_read_b128 v[172:175], v152 offset:17408
	ds_read_b128 v[176:179], v152 offset:18432
	ds_read_b128 v[180:183], v152 offset:19456
	ds_read_b128 v[184:187], v152 offset:20480
	ds_read_b128 v[188:191], v152 offset:21504
	ds_read_b128 v[192:195], v152 offset:22528
	ds_read_b128 v[196:199], v152 offset:23552
	global_load_lds_dwordx4 v128, s[30:31]
	s_mov_b32 m0, s42
	s_nop 0
	global_load_lds_dwordx4 v132, s[30:31]
	s_barrier
	s_waitcnt lgkmcnt(0)
	s_setprio 1
	s_waitcnt lgkmcnt(0)
	v_mfma_f32_16x16x32_bf16 v[60:63], v[144:147], v[168:171], v[60:63]
	v_mfma_f32_16x16x32_bf16 v[56:59], v[160:163], v[168:171], v[56:59]
	v_mfma_f32_16x16x32_bf16 v[44:47], v[144:147], v[176:179], v[44:47]
	v_mfma_f32_16x16x32_bf16 v[40:43], v[160:163], v[176:179], v[40:43]
	v_mfma_f32_16x16x32_bf16 v[28:31], v[144:147], v[184:187], v[28:31]
	v_mfma_f32_16x16x32_bf16 v[24:27], v[160:163], v[184:187], v[24:27]
	v_mfma_f32_16x16x32_bf16 v[12:15], v[144:147], v[192:195], v[12:15]
	v_mfma_f32_16x16x32_bf16 v[8:11], v[160:163], v[192:195], v[8:11]
	v_mfma_f32_16x16x32_bf16 v[60:63], v[156:159], v[172:175], v[60:63]
	v_mfma_f32_16x16x32_bf16 v[56:59], v[164:167], v[172:175], v[56:59]
	v_mfma_f32_16x16x32_bf16 v[44:47], v[156:159], v[180:183], v[44:47]
	v_mfma_f32_16x16x32_bf16 v[40:43], v[164:167], v[180:183], v[40:43]
	v_mfma_f32_16x16x32_bf16 v[28:31], v[156:159], v[188:191], v[28:31]
	v_mfma_f32_16x16x32_bf16 v[24:27], v[164:167], v[188:191], v[24:27]
	v_mfma_f32_16x16x32_bf16 v[12:15], v[156:159], v[196:199], v[12:15]
	v_mfma_f32_16x16x32_bf16 v[8:11], v[164:167], v[196:199], v[8:11]
	s_setprio 0
	s_barrier
	s_add_u32 s20, s28, 0xb0000
	s_addc_u32 s21, s29, 0
	s_add_i32 s60, s52, s40
	s_mov_b32 m0, s60
	s_nop 0
	global_load_lds_dwordx4 v130, s[20:21]
	s_add_i32 m0, s60, 0x2000
	s_nop 0
	global_load_lds_dwordx4 v134, s[20:21]
	s_waitcnt vmcnt(6)
	s_barrier
	s_setprio 1
	v_mfma_f32_16x16x32_bf16 v[52:55], v[200:203], v[168:171], v[52:55]
	v_mfma_f32_16x16x32_bf16 v[48:51], v[208:211], v[168:171], v[48:51]
	v_mfma_f32_16x16x32_bf16 v[36:39], v[200:203], v[176:179], v[36:39]
	v_mfma_f32_16x16x32_bf16 v[32:35], v[208:211], v[176:179], v[32:35]
	v_mfma_f32_16x16x32_bf16 v[20:23], v[200:203], v[184:187], v[20:23]
	v_mfma_f32_16x16x32_bf16 v[16:19], v[208:211], v[184:187], v[16:19]
	v_mfma_f32_16x16x32_bf16 v[4:7], v[200:203], v[192:195], v[4:7]
	v_mfma_f32_16x16x32_bf16 v[0:3], v[208:211], v[192:195], v[0:3]
	v_mfma_f32_16x16x32_bf16 v[52:55], v[204:207], v[172:175], v[52:55]
	v_mfma_f32_16x16x32_bf16 v[48:51], v[212:215], v[172:175], v[48:51]
	v_mfma_f32_16x16x32_bf16 v[36:39], v[204:207], v[180:183], v[36:39]
	v_mfma_f32_16x16x32_bf16 v[32:35], v[212:215], v[180:183], v[32:35]
	v_mfma_f32_16x16x32_bf16 v[20:23], v[204:207], v[188:191], v[20:23]
	v_mfma_f32_16x16x32_bf16 v[16:19], v[212:215], v[188:191], v[16:19]
	v_mfma_f32_16x16x32_bf16 v[4:7], v[204:207], v[196:199], v[4:7]
	v_mfma_f32_16x16x32_bf16 v[0:3], v[212:215], v[196:199], v[0:3]
	s_setprio 0
	s_add_i32 s60, 0, 0x18000
	v_add_u32_e32 v155, s60, v149
	s_barrier
	ds_read_b128 v[144:147], v155
	ds_read_b128 v[156:159], v155 offset:1024
	ds_read_b128 v[160:163], v155 offset:2048
	ds_read_b128 v[164:167], v155 offset:3072
	s_add_u32 s20, s30, 0xb0000
	s_addc_u32 s21, s31, 0
	s_mov_b32 m0, s43
	ds_read_b128 v[168:171], v152 offset:32768
	ds_read_b128 v[172:175], v152 offset:33792
	ds_read_b128 v[176:179], v152 offset:34816
	ds_read_b128 v[180:183], v152 offset:35840
	ds_read_b128 v[184:187], v152 offset:36864
	ds_read_b128 v[188:191], v152 offset:37888
	ds_read_b128 v[192:195], v152 offset:38912
	ds_read_b128 v[196:199], v152 offset:39936
	global_load_lds_dwordx4 v128, s[20:21]
	s_mov_b32 m0, s44
	s_nop 0
	global_load_lds_dwordx4 v132, s[20:21]
	s_waitcnt lgkmcnt(8)
	s_barrier
	s_waitcnt lgkmcnt(0)
	s_setprio 1
	s_waitcnt lgkmcnt(0)
	v_mfma_f32_16x16x32_bf16 v[124:127], v[144:147], v[168:171], v[124:127]
	v_mfma_f32_16x16x32_bf16 v[120:123], v[160:163], v[168:171], v[120:123]
	v_mfma_f32_16x16x32_bf16 v[108:111], v[144:147], v[176:179], v[108:111]
	v_mfma_f32_16x16x32_bf16 v[104:107], v[160:163], v[176:179], v[104:107]
	v_mfma_f32_16x16x32_bf16 v[92:95], v[144:147], v[184:187], v[92:95]
	v_mfma_f32_16x16x32_bf16 v[88:91], v[160:163], v[184:187], v[88:91]
	v_mfma_f32_16x16x32_bf16 v[76:79], v[144:147], v[192:195], v[76:79]
	v_mfma_f32_16x16x32_bf16 v[72:75], v[160:163], v[192:195], v[72:75]
	v_mfma_f32_16x16x32_bf16 v[124:127], v[156:159], v[172:175], v[124:127]
	v_mfma_f32_16x16x32_bf16 v[120:123], v[164:167], v[172:175], v[120:123]
	v_mfma_f32_16x16x32_bf16 v[108:111], v[156:159], v[180:183], v[108:111]
	v_mfma_f32_16x16x32_bf16 v[104:107], v[164:167], v[180:183], v[104:107]
	v_mfma_f32_16x16x32_bf16 v[92:95], v[156:159], v[188:191], v[92:95]
	v_mfma_f32_16x16x32_bf16 v[88:91], v[164:167], v[188:191], v[88:91]
	v_mfma_f32_16x16x32_bf16 v[76:79], v[156:159], v[196:199], v[76:79]
	v_mfma_f32_16x16x32_bf16 v[72:75], v[164:167], v[196:199], v[72:75]
	s_setprio 0
	s_barrier
	s_add_i32 s30, 0, 0x1c000
	s_add_i32 s20, s60, s40
	v_add_u32_e32 v155, s30, v149
	s_mov_b32 m0, s20
	ds_read_b128 v[200:203], v155
	ds_read_b128 v[204:207], v155 offset:1024
	ds_read_b128 v[208:211], v155 offset:2048
	ds_read_b128 v[212:215], v155 offset:3072
	global_load_lds_dwordx4 v130, s[80:81]
	s_add_i32 m0, s20, 0x2000
	s_nop 0
	global_load_lds_dwordx4 v134, s[80:81]
	s_barrier
	s_waitcnt lgkmcnt(0)
	s_setprio 1
	s_waitcnt lgkmcnt(0)
	v_mfma_f32_16x16x32_bf16 v[116:119], v[200:203], v[168:171], v[116:119]
	v_mfma_f32_16x16x32_bf16 v[112:115], v[208:211], v[168:171], v[112:115]
	v_mfma_f32_16x16x32_bf16 v[100:103], v[200:203], v[176:179], v[100:103]
	v_mfma_f32_16x16x32_bf16 v[96:99], v[208:211], v[176:179], v[96:99]
	v_mfma_f32_16x16x32_bf16 v[84:87], v[200:203], v[184:187], v[84:87]
	v_mfma_f32_16x16x32_bf16 v[80:83], v[208:211], v[184:187], v[80:83]
	v_mfma_f32_16x16x32_bf16 v[68:71], v[200:203], v[192:195], v[68:71]
	v_mfma_f32_16x16x32_bf16 v[64:67], v[208:211], v[192:195], v[64:67]
	v_mfma_f32_16x16x32_bf16 v[116:119], v[204:207], v[172:175], v[116:119]
	v_mfma_f32_16x16x32_bf16 v[112:115], v[212:215], v[172:175], v[112:115]
	v_mfma_f32_16x16x32_bf16 v[100:103], v[204:207], v[180:183], v[100:103]
	v_mfma_f32_16x16x32_bf16 v[96:99], v[212:215], v[180:183], v[96:99]
	v_mfma_f32_16x16x32_bf16 v[84:87], v[204:207], v[188:191], v[84:87]
	v_mfma_f32_16x16x32_bf16 v[80:83], v[212:215], v[188:191], v[80:83]
	v_mfma_f32_16x16x32_bf16 v[68:71], v[204:207], v[196:199], v[68:71]
	v_mfma_f32_16x16x32_bf16 v[64:67], v[212:215], v[196:199], v[64:67]
	s_setprio 0
	s_mov_b32 m0, s46
	s_barrier
	ds_read_b128 v[168:171], v152 offset:49152
	ds_read_b128 v[172:175], v152 offset:50176
	ds_read_b128 v[176:179], v152 offset:51200
	ds_read_b128 v[180:183], v152 offset:52224
	ds_read_b128 v[184:187], v152 offset:53248
	ds_read_b128 v[188:191], v152 offset:54272
	ds_read_b128 v[192:195], v152 offset:55296
	ds_read_b128 v[196:199], v152 offset:56320
	global_load_lds_dwordx4 v128, s[82:83]
	s_mov_b32 m0, s47
	s_nop 0
	global_load_lds_dwordx4 v132, s[82:83]
	s_barrier
	s_waitcnt lgkmcnt(0)
	s_setprio 1
	s_waitcnt lgkmcnt(0)
	v_mfma_f32_16x16x32_bf16 v[60:63], v[144:147], v[168:171], v[60:63]
	v_mfma_f32_16x16x32_bf16 v[56:59], v[160:163], v[168:171], v[56:59]
	v_mfma_f32_16x16x32_bf16 v[44:47], v[144:147], v[176:179], v[44:47]
	v_mfma_f32_16x16x32_bf16 v[40:43], v[160:163], v[176:179], v[40:43]
	v_mfma_f32_16x16x32_bf16 v[28:31], v[144:147], v[184:187], v[28:31]
	v_mfma_f32_16x16x32_bf16 v[24:27], v[160:163], v[184:187], v[24:27]
	v_mfma_f32_16x16x32_bf16 v[12:15], v[144:147], v[192:195], v[12:15]
	v_mfma_f32_16x16x32_bf16 v[8:11], v[160:163], v[192:195], v[8:11]
	v_mfma_f32_16x16x32_bf16 v[60:63], v[156:159], v[172:175], v[60:63]
	v_mfma_f32_16x16x32_bf16 v[56:59], v[164:167], v[172:175], v[56:59]
	v_mfma_f32_16x16x32_bf16 v[44:47], v[156:159], v[180:183], v[44:47]
	v_mfma_f32_16x16x32_bf16 v[40:43], v[164:167], v[180:183], v[40:43]
	v_mfma_f32_16x16x32_bf16 v[28:31], v[156:159], v[188:191], v[28:31]
	v_mfma_f32_16x16x32_bf16 v[24:27], v[164:167], v[188:191], v[24:27]
	v_mfma_f32_16x16x32_bf16 v[12:15], v[156:159], v[196:199], v[12:15]
	v_mfma_f32_16x16x32_bf16 v[8:11], v[164:167], v[196:199], v[8:11]
	s_setprio 0
	s_barrier
	s_add_u32 s20, s28, 0xb0080
	s_addc_u32 s21, s29, 0
	s_add_i32 s28, s30, s40
	s_mov_b32 m0, s28
	s_nop 0
	global_load_lds_dwordx4 v130, s[20:21]
	s_add_i32 m0, s28, 0x2000
	s_nop 0
	global_load_lds_dwordx4 v134, s[20:21]
	s_waitcnt vmcnt(6)
	s_barrier
	s_setprio 1
	v_mfma_f32_16x16x32_bf16 v[52:55], v[200:203], v[168:171], v[52:55]
	v_mfma_f32_16x16x32_bf16 v[48:51], v[208:211], v[168:171], v[48:51]
	v_mfma_f32_16x16x32_bf16 v[36:39], v[200:203], v[176:179], v[36:39]
	v_mfma_f32_16x16x32_bf16 v[32:35], v[208:211], v[176:179], v[32:35]
	v_mfma_f32_16x16x32_bf16 v[20:23], v[200:203], v[184:187], v[20:23]
	v_mfma_f32_16x16x32_bf16 v[16:19], v[208:211], v[184:187], v[16:19]
	v_mfma_f32_16x16x32_bf16 v[4:7], v[200:203], v[192:195], v[4:7]
	v_mfma_f32_16x16x32_bf16 v[0:3], v[208:211], v[192:195], v[0:3]
	v_mfma_f32_16x16x32_bf16 v[52:55], v[204:207], v[172:175], v[52:55]
	v_mfma_f32_16x16x32_bf16 v[48:51], v[212:215], v[172:175], v[48:51]
	v_mfma_f32_16x16x32_bf16 v[36:39], v[204:207], v[180:183], v[36:39]
	v_mfma_f32_16x16x32_bf16 v[32:35], v[212:215], v[180:183], v[32:35]
	v_mfma_f32_16x16x32_bf16 v[20:23], v[204:207], v[188:191], v[20:23]
	v_mfma_f32_16x16x32_bf16 v[16:19], v[212:215], v[188:191], v[16:19]
	v_mfma_f32_16x16x32_bf16 v[4:7], v[204:207], v[196:199], v[4:7]
	v_mfma_f32_16x16x32_bf16 v[0:3], v[212:215], v[196:199], v[0:3]
	s_setprio 0
	s_add_i32 s59, s59, 2
	s_add_u32 s57, s57, 0x100
	s_addc_u32 s58, s58, 0
	s_cmp_gt_u32 s59, 41
	s_mov_b64 s[20:21], s[26:27]
	s_barrier
	s_cbranch_scc0 .LBB0_248
	v_lshl_add_u32 v146, s56, 8, v148
	v_ashrrev_i32_e32 v147, 31, v146
	v_lshl_or_b32 v144, s12, 8, v150
	v_lshlrev_b64 v[156:157], 11, v[146:147]
	v_ashrrev_i32_e32 v145, 31, v144
	v_lshl_add_u64 v[156:157], s[14:15], 0, v[156:157]
	v_lshl_add_u64 v[166:167], v[144:145], 1, v[156:157]
	global_load_dwordx4 v[158:161], v[166:167], off
	global_load_dwordx4 v[162:165], v[166:167], off offset:256
	s_mov_b64 s[84:85], 0x8000
	s_mov_b64 s[86:87], 0x28000
	v_lshl_add_u64 v[232:233], v[166:167], 0, s[84:85]
	global_load_dwordx4 v[176:179], v[232:233], off
	global_load_dwordx4 v[180:183], v[232:233], off offset:256
	v_lshl_add_u64 v[232:233], v[232:233], 0, s[84:85]
	global_load_dwordx4 v[184:187], v[232:233], off
	global_load_dwordx4 v[188:191], v[232:233], off offset:256
	v_lshl_add_u64 v[232:233], v[232:233], 0, s[84:85]
	global_load_dwordx4 v[192:195], v[232:233], off
	global_load_dwordx4 v[196:199], v[232:233], off offset:256
	v_lshl_add_u64 v[232:233], v[232:233], 0, s[86:87]
	global_load_dwordx4 v[200:203], v[232:233], off
	global_load_dwordx4 v[204:207], v[232:233], off offset:256
	v_lshl_add_u64 v[232:233], v[232:233], 0, s[84:85]
	global_load_dwordx4 v[208:211], v[232:233], off
	global_load_dwordx4 v[212:215], v[232:233], off offset:256
	v_lshl_add_u64 v[232:233], v[232:233], 0, s[84:85]
	global_load_dwordx4 v[216:219], v[232:233], off
	global_load_dwordx4 v[220:223], v[232:233], off offset:256
	v_lshl_add_u64 v[232:233], v[232:233], 0, s[84:85]
	global_load_dwordx4 v[224:227], v[232:233], off
	global_load_dwordx4 v[228:231], v[232:233], off offset:256
	s_cmpk_gt_u32 s35, 0xff
	s_cbranch_scc1 .Lg248_nox
	s_barrier
.Lg248_nox:
	v_and_b32_e32 v156, 64, v154
	v_xor_b32_e32 v155, 16, v154
	v_add_u32_e32 v156, 64, v156
	v_xor_b32_e32 v157, 32, v154
	v_cmp_lt_i32_e32 vcc, v155, v156
	s_lshl_b32 s20, s12, 2
	s_ashr_i32 s21, s20, 31
	v_cndmask_b32_e32 v155, v154, v155, vcc
	v_cmp_lt_i32_e32 vcc, v157, v156
	v_lshlrev_b32_e32 v156, 2, v155
	s_waitcnt vmcnt(14)
	v_lshlrev_b32_e32 v168, 16, v158
	v_and_b32_e32 v169, 0xffff0000, v158
	v_lshlrev_b32_e32 v158, 16, v159
	v_and_b32_e32 v159, 0xffff0000, v159
	v_lshlrev_b32_e32 v172, 16, v162
	v_and_b32_e32 v173, 0xffff0000, v162
	v_lshlrev_b32_e32 v162, 16, v163
	v_and_b32_e32 v163, 0xffff0000, v163
	v_cndmask_b32_e32 v157, v154, v157, vcc
	v_lshlrev_b32_e32 v170, 16, v160
	v_and_b32_e32 v171, 0xffff0000, v160
	v_lshlrev_b32_e32 v160, 16, v161
	v_and_b32_e32 v161, 0xffff0000, v161
	v_lshlrev_b32_e32 v174, 16, v164
	v_and_b32_e32 v175, 0xffff0000, v164
	v_lshlrev_b32_e32 v164, 16, v165
	v_and_b32_e32 v165, 0xffff0000, v165
	v_pk_fma_f32 v[126:127], v[126:127], 0.5, v[158:159] op_sel_hi:[1,0,1]
	v_pk_fma_f32 v[124:125], v[124:125], 0.5, v[168:169] op_sel_hi:[1,0,1]
	v_pk_fma_f32 v[118:119], v[118:119], 0.5, v[162:163] op_sel_hi:[1,0,1]
	v_pk_fma_f32 v[116:117], v[116:117], 0.5, v[172:173] op_sel_hi:[1,0,1]
	v_lshlrev_b32_e32 v155, 2, v157
	v_pk_fma_f32 v[122:123], v[122:123], 0.5, v[160:161] op_sel_hi:[1,0,1]
	v_pk_fma_f32 v[120:121], v[120:121], 0.5, v[170:171] op_sel_hi:[1,0,1]
	v_pk_fma_f32 v[158:159], v[114:115], 0.5, v[164:165] op_sel_hi:[1,0,1]
	v_pk_fma_f32 v[160:161], v[112:113], 0.5, v[174:175] op_sel_hi:[1,0,1]
	v_mul_f32_e32 v114, v125, v125
	v_mul_f32_e32 v115, v127, v127
	v_mul_f32_e32 v157, v117, v117
	v_mul_f32_e32 v162, v119, v119
	v_cvt_pk_bf16_f32 v112, v124, v125
	v_mul_f32_e32 v125, v121, v121
	v_mul_f32_e32 v163, v161, v161
	v_fmac_f32_e32 v114, v124, v124
	v_fmac_f32_e32 v115, v126, v126
	v_fmac_f32_e32 v157, v116, v116
	v_fmac_f32_e32 v162, v118, v118
	v_cvt_pk_bf16_f32 v113, v126, v127
	v_mul_f32_e32 v127, v123, v123
	v_mul_f32_e32 v164, v159, v159
	v_fmac_f32_e32 v125, v120, v120
	v_fmac_f32_e32 v163, v160, v160
	v_add_f32_e32 v114, v114, v115
	v_add_f32_e32 v115, v157, v162
	v_fmac_f32_e32 v127, v122, v122
	v_fmac_f32_e32 v164, v158, v158
	v_add_f32_e32 v114, v125, v114
	v_add_f32_e32 v115, v163, v115
	v_add_f32_e32 v114, v127, v114
	v_add_f32_e32 v115, v164, v115
	v_add_f32_e32 v124, v114, v115
	ds_bpermute_b32 v125, v156, v124
	v_cvt_pk_bf16_f32 v114, v120, v121
	v_cvt_pk_bf16_f32 v115, v122, v123
	global_store_dwordx4 v[166:167], v[112:115], off
	s_waitcnt lgkmcnt(0)
	s_nop 0
	v_add_f32_e32 v112, v124, v125
	ds_bpermute_b32 v113, v155, v112
	v_cvt_pk_bf16_f32 v114, v116, v117
	v_cvt_pk_bf16_f32 v115, v118, v119
	v_cvt_pk_bf16_f32 v116, v160, v161
	v_cvt_pk_bf16_f32 v117, v158, v159
	global_store_dwordx4 v[166:167], v[114:117], off offset:256
	s_and_saveexec_b64 s[26:27], s[4:5]
	s_cbranch_execz .LBB0_251
	v_lshlrev_b64 v[114:115], 6, v[146:147]
	v_lshl_add_u64 v[114:115], s[16:17], 0, v[114:115]
	v_lshl_add_u64 v[114:115], s[20:21], 2, v[114:115]
	s_lshl_b32 s12, s45, 2
	v_lshl_add_u64 v[114:115], v[114:115], 0, s[12:13]
	s_waitcnt lgkmcnt(0)
	v_add_f32_e32 v112, v112, v113
	global_store_dword v[114:115], v112, off
.LBB0_251:
	s_or_b64 exec, exec, s[26:27]
	v_or_b32_e32 v112, 16, v146
	s_waitcnt lgkmcnt(0)
	v_ashrrev_i32_e32 v113, 31, v112
	v_lshlrev_b64 v[114:115], 11, v[112:113]
	v_lshl_add_u64 v[114:115], s[14:15], 0, v[114:115]
	v_lshl_add_u64 v[122:123], v[144:145], 1, v[114:115]
	s_waitcnt vmcnt(15)
	v_lshlrev_b32_e32 v124, 16, v176
	v_and_b32_e32 v125, 0xffff0000, v176
	v_lshlrev_b32_e32 v114, 16, v177
	v_and_b32_e32 v115, 0xffff0000, v177
	s_waitcnt vmcnt(14)
	v_lshlrev_b32_e32 v158, 16, v180
	v_and_b32_e32 v159, 0xffff0000, v180
	v_lshlrev_b32_e32 v118, 16, v181
	v_and_b32_e32 v119, 0xffff0000, v181
	v_lshlrev_b32_e32 v126, 16, v178
	v_and_b32_e32 v127, 0xffff0000, v178
	v_lshlrev_b32_e32 v116, 16, v179
	v_and_b32_e32 v117, 0xffff0000, v179
	v_lshlrev_b32_e32 v160, 16, v182
	v_and_b32_e32 v161, 0xffff0000, v182
	v_lshlrev_b32_e32 v120, 16, v183
	v_and_b32_e32 v121, 0xffff0000, v183
	v_pk_fma_f32 v[110:111], v[110:111], 0.5, v[114:115] op_sel_hi:[1,0,1]
	v_pk_fma_f32 v[108:109], v[108:109], 0.5, v[124:125] op_sel_hi:[1,0,1]
	v_pk_fma_f32 v[102:103], v[102:103], 0.5, v[118:119] op_sel_hi:[1,0,1]
	v_pk_fma_f32 v[100:101], v[100:101], 0.5, v[158:159] op_sel_hi:[1,0,1]
	v_pk_fma_f32 v[106:107], v[106:107], 0.5, v[116:117] op_sel_hi:[1,0,1]
	v_pk_fma_f32 v[104:105], v[104:105], 0.5, v[126:127] op_sel_hi:[1,0,1]
	v_pk_fma_f32 v[114:115], v[98:99], 0.5, v[120:121] op_sel_hi:[1,0,1]
	v_pk_fma_f32 v[116:117], v[96:97], 0.5, v[160:161] op_sel_hi:[1,0,1]
	v_mul_f32_e32 v98, v109, v109
	v_mul_f32_e32 v99, v111, v111
	v_mul_f32_e32 v118, v101, v101
	v_mul_f32_e32 v119, v103, v103
	v_cvt_pk_bf16_f32 v96, v108, v109
	v_mul_f32_e32 v109, v105, v105
	v_mul_f32_e32 v120, v117, v117
	v_fmac_f32_e32 v98, v108, v108
	v_fmac_f32_e32 v99, v110, v110
	v_fmac_f32_e32 v118, v100, v100
	v_fmac_f32_e32 v119, v102, v102
	v_cvt_pk_bf16_f32 v97, v110, v111
	v_mul_f32_e32 v111, v107, v107
	v_mul_f32_e32 v121, v115, v115
	v_fmac_f32_e32 v109, v104, v104
	v_fmac_f32_e32 v120, v116, v116
	v_add_f32_e32 v98, v98, v99
	v_add_f32_e32 v99, v118, v119
	v_fmac_f32_e32 v111, v106, v106
	v_fmac_f32_e32 v121, v114, v114
	v_add_f32_e32 v98, v109, v98
	v_add_f32_e32 v99, v120, v99
	v_add_f32_e32 v98, v111, v98
	v_add_f32_e32 v99, v121, v99
	v_add_f32_e32 v108, v98, v99
	ds_bpermute_b32 v109, v156, v108
	v_cvt_pk_bf16_f32 v98, v104, v105
	v_cvt_pk_bf16_f32 v99, v106, v107
	global_store_dwordx4 v[122:123], v[96:99], off
	s_waitcnt lgkmcnt(0)
	s_nop 0
	v_add_f32_e32 v96, v108, v109
	ds_bpermute_b32 v97, v155, v96
	v_cvt_pk_bf16_f32 v98, v100, v101
	v_cvt_pk_bf16_f32 v99, v102, v103
	v_cvt_pk_bf16_f32 v100, v116, v117
	v_cvt_pk_bf16_f32 v101, v114, v115
	global_store_dwordx4 v[122:123], v[98:101], off offset:256
	s_and_saveexec_b64 s[26:27], s[4:5]
	s_cbranch_execz .LBB0_253
	v_lshlrev_b64 v[98:99], 6, v[112:113]
	v_lshl_add_u64 v[98:99], s[16:17], 0, v[98:99]
	v_lshl_add_u64 v[98:99], s[20:21], 2, v[98:99]
	s_lshl_b32 s12, s45, 2
	v_lshl_add_u64 v[98:99], v[98:99], 0, s[12:13]
	s_waitcnt lgkmcnt(0)
	v_add_f32_e32 v96, v96, v97
	global_store_dword v[98:99], v96, off
.LBB0_253:
	s_or_b64 exec, exec, s[26:27]
	v_or_b32_e32 v96, 32, v146
	s_waitcnt lgkmcnt(0)
	v_ashrrev_i32_e32 v97, 31, v96
	v_lshlrev_b64 v[98:99], 11, v[96:97]
	v_lshl_add_u64 v[98:99], s[14:15], 0, v[98:99]
	v_lshl_add_u64 v[106:107], v[144:145], 1, v[98:99]
	s_waitcnt vmcnt(15)
	v_lshlrev_b32_e32 v108, 16, v184
	v_and_b32_e32 v109, 0xffff0000, v184
	v_lshlrev_b32_e32 v98, 16, v185
	v_and_b32_e32 v99, 0xffff0000, v185
	s_waitcnt vmcnt(14)
	v_lshlrev_b32_e32 v112, 16, v188
	v_and_b32_e32 v113, 0xffff0000, v188
	v_lshlrev_b32_e32 v102, 16, v189
	v_and_b32_e32 v103, 0xffff0000, v189
	v_lshlrev_b32_e32 v110, 16, v186
	v_and_b32_e32 v111, 0xffff0000, v186
	v_lshlrev_b32_e32 v100, 16, v187
	v_and_b32_e32 v101, 0xffff0000, v187
	v_lshlrev_b32_e32 v114, 16, v190
	v_and_b32_e32 v115, 0xffff0000, v190
	v_lshlrev_b32_e32 v104, 16, v191
	v_and_b32_e32 v105, 0xffff0000, v191
	v_pk_fma_f32 v[94:95], v[94:95], 0.5, v[98:99] op_sel_hi:[1,0,1]
	v_pk_fma_f32 v[92:93], v[92:93], 0.5, v[108:109] op_sel_hi:[1,0,1]
	v_pk_fma_f32 v[86:87], v[86:87], 0.5, v[102:103] op_sel_hi:[1,0,1]
	v_pk_fma_f32 v[84:85], v[84:85], 0.5, v[112:113] op_sel_hi:[1,0,1]
	v_pk_fma_f32 v[90:91], v[90:91], 0.5, v[100:101] op_sel_hi:[1,0,1]
	v_pk_fma_f32 v[88:89], v[88:89], 0.5, v[110:111] op_sel_hi:[1,0,1]
	v_pk_fma_f32 v[98:99], v[82:83], 0.5, v[104:105] op_sel_hi:[1,0,1]
	v_pk_fma_f32 v[100:101], v[80:81], 0.5, v[114:115] op_sel_hi:[1,0,1]
	v_mul_f32_e32 v82, v93, v93
	v_mul_f32_e32 v83, v95, v95
	v_mul_f32_e32 v102, v85, v85
	v_mul_f32_e32 v103, v87, v87
	v_cvt_pk_bf16_f32 v80, v92, v93
	v_mul_f32_e32 v93, v89, v89
	v_mul_f32_e32 v104, v101, v101
	v_fmac_f32_e32 v82, v92, v92
	v_fmac_f32_e32 v83, v94, v94
	v_fmac_f32_e32 v102, v84, v84
	v_fmac_f32_e32 v103, v86, v86
	v_cvt_pk_bf16_f32 v81, v94, v95
	v_mul_f32_e32 v95, v91, v91
	v_mul_f32_e32 v105, v99, v99
	v_fmac_f32_e32 v93, v88, v88
	v_fmac_f32_e32 v104, v100, v100
	v_add_f32_e32 v82, v82, v83
	v_add_f32_e32 v83, v102, v103
	v_fmac_f32_e32 v95, v90, v90
	v_fmac_f32_e32 v105, v98, v98
	v_add_f32_e32 v82, v93, v82
	v_add_f32_e32 v83, v104, v83
	v_add_f32_e32 v82, v95, v82
	v_add_f32_e32 v83, v105, v83
	v_add_f32_e32 v92, v82, v83
	ds_bpermute_b32 v93, v156, v92
	v_cvt_pk_bf16_f32 v82, v88, v89
	v_cvt_pk_bf16_f32 v83, v90, v91
	global_store_dwordx4 v[106:107], v[80:83], off
	s_waitcnt lgkmcnt(0)
	s_nop 0
	v_add_f32_e32 v80, v92, v93
	ds_bpermute_b32 v81, v155, v80
	v_cvt_pk_bf16_f32 v82, v84, v85
	v_cvt_pk_bf16_f32 v83, v86, v87
	v_cvt_pk_bf16_f32 v84, v100, v101
	v_cvt_pk_bf16_f32 v85, v98, v99
	global_store_dwordx4 v[106:107], v[82:85], off offset:256
	s_and_saveexec_b64 s[26:27], s[4:5]
	s_cbranch_execz .LBB0_255
	v_lshlrev_b64 v[82:83], 6, v[96:97]
	v_lshl_add_u64 v[82:83], s[16:17], 0, v[82:83]
	v_lshl_add_u64 v[82:83], s[20:21], 2, v[82:83]
	s_lshl_b32 s12, s45, 2
	v_lshl_add_u64 v[82:83], v[82:83], 0, s[12:13]
	s_waitcnt lgkmcnt(0)
	v_add_f32_e32 v80, v80, v81
	global_store_dword v[82:83], v80, off
.LBB0_255:
	s_or_b64 exec, exec, s[26:27]
	v_or_b32_e32 v80, 48, v146
	s_waitcnt lgkmcnt(0)
	v_ashrrev_i32_e32 v81, 31, v80
	v_lshlrev_b64 v[82:83], 11, v[80:81]
	v_lshl_add_u64 v[82:83], s[14:15], 0, v[82:83]
	v_lshl_add_u64 v[90:91], v[144:145], 1, v[82:83]
	s_waitcnt vmcnt(15)
	v_lshlrev_b32_e32 v92, 16, v192
	v_and_b32_e32 v93, 0xffff0000, v192
	v_lshlrev_b32_e32 v82, 16, v193
	v_and_b32_e32 v83, 0xffff0000, v193
	s_waitcnt vmcnt(14)
	v_lshlrev_b32_e32 v96, 16, v196
	v_and_b32_e32 v97, 0xffff0000, v196
	v_lshlrev_b32_e32 v86, 16, v197
	v_and_b32_e32 v87, 0xffff0000, v197
	v_lshlrev_b32_e32 v94, 16, v194
	v_and_b32_e32 v95, 0xffff0000, v194
	v_lshlrev_b32_e32 v84, 16, v195
	v_and_b32_e32 v85, 0xffff0000, v195
	v_lshlrev_b32_e32 v98, 16, v198
	v_and_b32_e32 v99, 0xffff0000, v198
	v_lshlrev_b32_e32 v88, 16, v199
	v_and_b32_e32 v89, 0xffff0000, v199
	v_pk_fma_f32 v[78:79], v[78:79], 0.5, v[82:83] op_sel_hi:[1,0,1]
	v_pk_fma_f32 v[76:77], v[76:77], 0.5, v[92:93] op_sel_hi:[1,0,1]
	v_pk_fma_f32 v[70:71], v[70:71], 0.5, v[86:87] op_sel_hi:[1,0,1]
	v_pk_fma_f32 v[68:69], v[68:69], 0.5, v[96:97] op_sel_hi:[1,0,1]
	v_pk_fma_f32 v[74:75], v[74:75], 0.5, v[84:85] op_sel_hi:[1,0,1]
	v_pk_fma_f32 v[72:73], v[72:73], 0.5, v[94:95] op_sel_hi:[1,0,1]
	v_pk_fma_f32 v[82:83], v[66:67], 0.5, v[88:89] op_sel_hi:[1,0,1]
	v_pk_fma_f32 v[84:85], v[64:65], 0.5, v[98:99] op_sel_hi:[1,0,1]
	v_mul_f32_e32 v66, v77, v77
	v_mul_f32_e32 v67, v79, v79
	v_mul_f32_e32 v86, v69, v69
	v_mul_f32_e32 v87, v71, v71
	v_cvt_pk_bf16_f32 v64, v76, v77
	v_mul_f32_e32 v77, v73, v73
	v_mul_f32_e32 v88, v85, v85
	v_fmac_f32_e32 v66, v76, v76
	v_fmac_f32_e32 v67, v78, v78
	v_fmac_f32_e32 v86, v68, v68
	v_fmac_f32_e32 v87, v70, v70
	v_cvt_pk_bf16_f32 v65, v78, v79
	v_mul_f32_e32 v79, v75, v75
	v_mul_f32_e32 v89, v83, v83
	v_fmac_f32_e32 v77, v72, v72
	v_fmac_f32_e32 v88, v84, v84
	v_add_f32_e32 v66, v66, v67
	v_add_f32_e32 v67, v86, v87
	v_fmac_f32_e32 v79, v74, v74
	v_fmac_f32_e32 v89, v82, v82
	v_add_f32_e32 v66, v77, v66
	v_add_f32_e32 v67, v88, v67
	v_add_f32_e32 v66, v79, v66
	v_add_f32_e32 v67, v89, v67
	v_add_f32_e32 v76, v66, v67
	ds_bpermute_b32 v77, v156, v76
	v_cvt_pk_bf16_f32 v66, v72, v73
	v_cvt_pk_bf16_f32 v67, v74, v75
	global_store_dwordx4 v[90:91], v[64:67], off
	s_waitcnt lgkmcnt(0)
	s_nop 0
	v_add_f32_e32 v64, v76, v77
	ds_bpermute_b32 v65, v155, v64
	v_cvt_pk_bf16_f32 v66, v68, v69
	v_cvt_pk_bf16_f32 v67, v70, v71
	v_cvt_pk_bf16_f32 v68, v84, v85
	v_cvt_pk_bf16_f32 v69, v82, v83
	global_store_dwordx4 v[90:91], v[66:69], off offset:256
	s_and_saveexec_b64 s[26:27], s[4:5]
	s_cbranch_execz .LBB0_257
	v_lshlrev_b64 v[66:67], 6, v[80:81]
	v_lshl_add_u64 v[66:67], s[16:17], 0, v[66:67]
	v_lshl_add_u64 v[66:67], s[20:21], 2, v[66:67]
	s_lshl_b32 s12, s45, 2
	v_lshl_add_u64 v[66:67], v[66:67], 0, s[12:13]
	s_waitcnt lgkmcnt(0)
	v_add_f32_e32 v64, v64, v65
	global_store_dword v[66:67], v64, off
.LBB0_257:
	s_or_b64 exec, exec, s[26:27]
	v_add_u32_e32 v64, 0x80, v146
	s_waitcnt lgkmcnt(0)
	v_ashrrev_i32_e32 v65, 31, v64
	v_lshlrev_b64 v[66:67], 11, v[64:65]
	v_lshl_add_u64 v[66:67], s[14:15], 0, v[66:67]
	v_lshl_add_u64 v[74:75], v[144:145], 1, v[66:67]
	s_waitcnt vmcnt(15)
	v_lshlrev_b32_e32 v76, 16, v200
	v_and_b32_e32 v77, 0xffff0000, v200
	v_lshlrev_b32_e32 v66, 16, v201
	v_and_b32_e32 v67, 0xffff0000, v201
	s_waitcnt vmcnt(14)
	v_lshlrev_b32_e32 v80, 16, v204
	v_and_b32_e32 v81, 0xffff0000, v204
	v_lshlrev_b32_e32 v70, 16, v205
	v_and_b32_e32 v71, 0xffff0000, v205
	v_lshlrev_b32_e32 v78, 16, v202
	v_and_b32_e32 v79, 0xffff0000, v202
	v_lshlrev_b32_e32 v68, 16, v203
	v_and_b32_e32 v69, 0xffff0000, v203
	v_lshlrev_b32_e32 v82, 16, v206
	v_and_b32_e32 v83, 0xffff0000, v206
	v_lshlrev_b32_e32 v72, 16, v207
	v_and_b32_e32 v73, 0xffff0000, v207
	v_pk_fma_f32 v[62:63], v[62:63], 0.5, v[66:67] op_sel_hi:[1,0,1]
	v_pk_fma_f32 v[60:61], v[60:61], 0.5, v[76:77] op_sel_hi:[1,0,1]
	v_pk_fma_f32 v[54:55], v[54:55], 0.5, v[70:71] op_sel_hi:[1,0,1]
	v_pk_fma_f32 v[52:53], v[52:53], 0.5, v[80:81] op_sel_hi:[1,0,1]
	v_pk_fma_f32 v[58:59], v[58:59], 0.5, v[68:69] op_sel_hi:[1,0,1]
	v_pk_fma_f32 v[56:57], v[56:57], 0.5, v[78:79] op_sel_hi:[1,0,1]
	v_pk_fma_f32 v[66:67], v[50:51], 0.5, v[72:73] op_sel_hi:[1,0,1]
	v_pk_fma_f32 v[68:69], v[48:49], 0.5, v[82:83] op_sel_hi:[1,0,1]
	v_mul_f32_e32 v50, v61, v61
	v_mul_f32_e32 v51, v63, v63
	v_mul_f32_e32 v70, v53, v53
	v_mul_f32_e32 v71, v55, v55
	v_cvt_pk_bf16_f32 v48, v60, v61
	v_mul_f32_e32 v61, v57, v57
	v_mul_f32_e32 v72, v69, v69
	v_fmac_f32_e32 v50, v60, v60
	v_fmac_f32_e32 v51, v62, v62
	v_fmac_f32_e32 v70, v52, v52
	v_fmac_f32_e32 v71, v54, v54
	v_cvt_pk_bf16_f32 v49, v62, v63
	v_mul_f32_e32 v63, v59, v59
	v_mul_f32_e32 v73, v67, v67
	v_fmac_f32_e32 v61, v56, v56
	v_fmac_f32_e32 v72, v68, v68
	v_add_f32_e32 v50, v50, v51
	v_add_f32_e32 v51, v70, v71
	v_fmac_f32_e32 v63, v58, v58
	v_fmac_f32_e32 v73, v66, v66
	v_add_f32_e32 v50, v61, v50
	v_add_f32_e32 v51, v72, v51
	v_add_f32_e32 v50, v63, v50
	v_add_f32_e32 v51, v73, v51
	v_add_f32_e32 v60, v50, v51
	ds_bpermute_b32 v61, v156, v60
	v_cvt_pk_bf16_f32 v50, v56, v57
	v_cvt_pk_bf16_f32 v51, v58, v59
	global_store_dwordx4 v[74:75], v[48:51], off
	s_waitcnt lgkmcnt(0)
	s_nop 0
	v_add_f32_e32 v48, v60, v61
	ds_bpermute_b32 v49, v155, v48
	v_cvt_pk_bf16_f32 v50, v52, v53
	v_cvt_pk_bf16_f32 v51, v54, v55
	v_cvt_pk_bf16_f32 v52, v68, v69
	v_cvt_pk_bf16_f32 v53, v66, v67
	global_store_dwordx4 v[74:75], v[50:53], off offset:256
	s_and_saveexec_b64 s[26:27], s[4:5]
	s_cbranch_execz .LBB0_259
	v_lshlrev_b64 v[50:51], 6, v[64:65]
	v_lshl_add_u64 v[50:51], s[16:17], 0, v[50:51]
	v_lshl_add_u64 v[50:51], s[20:21], 2, v[50:51]
	s_lshl_b32 s12, s45, 2
	v_lshl_add_u64 v[50:51], v[50:51], 0, s[12:13]
	s_waitcnt lgkmcnt(0)
	v_add_f32_e32 v48, v48, v49
	global_store_dword v[50:51], v48, off
.LBB0_259:
	s_or_b64 exec, exec, s[26:27]
	v_add_u32_e32 v48, 0x90, v146
	s_waitcnt lgkmcnt(0)
	v_ashrrev_i32_e32 v49, 31, v48
	v_lshlrev_b64 v[50:51], 11, v[48:49]
	v_lshl_add_u64 v[50:51], s[14:15], 0, v[50:51]
	v_lshl_add_u64 v[58:59], v[144:145], 1, v[50:51]
	s_waitcnt vmcnt(15)
	v_lshlrev_b32_e32 v60, 16, v208
	v_and_b32_e32 v61, 0xffff0000, v208
	v_lshlrev_b32_e32 v50, 16, v209
	v_and_b32_e32 v51, 0xffff0000, v209
	s_waitcnt vmcnt(14)
	v_lshlrev_b32_e32 v64, 16, v212
	v_and_b32_e32 v65, 0xffff0000, v212
	v_lshlrev_b32_e32 v54, 16, v213
	v_and_b32_e32 v55, 0xffff0000, v213
	v_lshlrev_b32_e32 v62, 16, v210
	v_and_b32_e32 v63, 0xffff0000, v210
	v_lshlrev_b32_e32 v52, 16, v211
	v_and_b32_e32 v53, 0xffff0000, v211
	v_lshlrev_b32_e32 v66, 16, v214
	v_and_b32_e32 v67, 0xffff0000, v214
	v_lshlrev_b32_e32 v56, 16, v215
	v_and_b32_e32 v57, 0xffff0000, v215
	v_pk_fma_f32 v[46:47], v[46:47], 0.5, v[50:51] op_sel_hi:[1,0,1]
	v_pk_fma_f32 v[44:45], v[44:45], 0.5, v[60:61] op_sel_hi:[1,0,1]
	v_pk_fma_f32 v[38:39], v[38:39], 0.5, v[54:55] op_sel_hi:[1,0,1]
	v_pk_fma_f32 v[36:37], v[36:37], 0.5, v[64:65] op_sel_hi:[1,0,1]
	v_pk_fma_f32 v[42:43], v[42:43], 0.5, v[52:53] op_sel_hi:[1,0,1]
	v_pk_fma_f32 v[40:41], v[40:41], 0.5, v[62:63] op_sel_hi:[1,0,1]
	v_pk_fma_f32 v[50:51], v[34:35], 0.5, v[56:57] op_sel_hi:[1,0,1]
	v_pk_fma_f32 v[52:53], v[32:33], 0.5, v[66:67] op_sel_hi:[1,0,1]
	v_mul_f32_e32 v34, v45, v45
	v_mul_f32_e32 v35, v47, v47
	v_mul_f32_e32 v54, v37, v37
	v_mul_f32_e32 v55, v39, v39
	v_cvt_pk_bf16_f32 v32, v44, v45
	v_mul_f32_e32 v45, v41, v41
	v_mul_f32_e32 v56, v53, v53
	v_fmac_f32_e32 v34, v44, v44
	v_fmac_f32_e32 v35, v46, v46
	v_fmac_f32_e32 v54, v36, v36
	v_fmac_f32_e32 v55, v38, v38
	v_cvt_pk_bf16_f32 v33, v46, v47
	v_mul_f32_e32 v47, v43, v43
	v_mul_f32_e32 v57, v51, v51
	v_fmac_f32_e32 v45, v40, v40
	v_fmac_f32_e32 v56, v52, v52
	v_add_f32_e32 v34, v34, v35
	v_add_f32_e32 v35, v54, v55
	v_fmac_f32_e32 v47, v42, v42
	v_fmac_f32_e32 v57, v50, v50
	v_add_f32_e32 v34, v45, v34
	v_add_f32_e32 v35, v56, v35
	v_add_f32_e32 v34, v47, v34
	v_add_f32_e32 v35, v57, v35
	v_add_f32_e32 v44, v34, v35
	ds_bpermute_b32 v45, v156, v44
	v_cvt_pk_bf16_f32 v34, v40, v41
	v_cvt_pk_bf16_f32 v35, v42, v43
	global_store_dwordx4 v[58:59], v[32:35], off
	s_waitcnt lgkmcnt(0)
	s_nop 0
	v_add_f32_e32 v32, v44, v45
	ds_bpermute_b32 v33, v155, v32
	v_cvt_pk_bf16_f32 v34, v36, v37
	v_cvt_pk_bf16_f32 v35, v38, v39
	v_cvt_pk_bf16_f32 v36, v52, v53
	v_cvt_pk_bf16_f32 v37, v50, v51
	global_store_dwordx4 v[58:59], v[34:37], off offset:256
	s_and_saveexec_b64 s[26:27], s[4:5]
	s_cbranch_execz .LBB0_261
	v_lshlrev_b64 v[34:35], 6, v[48:49]
	v_lshl_add_u64 v[34:35], s[16:17], 0, v[34:35]
	v_lshl_add_u64 v[34:35], s[20:21], 2, v[34:35]
	s_lshl_b32 s12, s45, 2
	v_lshl_add_u64 v[34:35], v[34:35], 0, s[12:13]
	s_waitcnt lgkmcnt(0)
	v_add_f32_e32 v32, v32, v33
	global_store_dword v[34:35], v32, off
.LBB0_261:
	s_or_b64 exec, exec, s[26:27]
	v_add_u32_e32 v32, 0xa0, v146
	s_waitcnt lgkmcnt(0)
	v_ashrrev_i32_e32 v33, 31, v32
	v_lshlrev_b64 v[34:35], 11, v[32:33]
	v_lshl_add_u64 v[34:35], s[14:15], 0, v[34:35]
	v_lshl_add_u64 v[42:43], v[144:145], 1, v[34:35]
	s_waitcnt vmcnt(15)
	v_lshlrev_b32_e32 v44, 16, v216
	v_and_b32_e32 v45, 0xffff0000, v216
	v_lshlrev_b32_e32 v34, 16, v217
	v_and_b32_e32 v35, 0xffff0000, v217
	s_waitcnt vmcnt(14)
	v_lshlrev_b32_e32 v48, 16, v220
	v_and_b32_e32 v49, 0xffff0000, v220
	v_lshlrev_b32_e32 v38, 16, v221
	v_and_b32_e32 v39, 0xffff0000, v221
	v_lshlrev_b32_e32 v46, 16, v218
	v_and_b32_e32 v47, 0xffff0000, v218
	v_lshlrev_b32_e32 v36, 16, v219
	v_and_b32_e32 v37, 0xffff0000, v219
	v_lshlrev_b32_e32 v50, 16, v222
	v_and_b32_e32 v51, 0xffff0000, v222
	v_lshlrev_b32_e32 v40, 16, v223
	v_and_b32_e32 v41, 0xffff0000, v223
	v_pk_fma_f32 v[30:31], v[30:31], 0.5, v[34:35] op_sel_hi:[1,0,1]
	v_pk_fma_f32 v[28:29], v[28:29], 0.5, v[44:45] op_sel_hi:[1,0,1]
	v_pk_fma_f32 v[22:23], v[22:23], 0.5, v[38:39] op_sel_hi:[1,0,1]
	v_pk_fma_f32 v[20:21], v[20:21], 0.5, v[48:49] op_sel_hi:[1,0,1]
	v_pk_fma_f32 v[26:27], v[26:27], 0.5, v[36:37] op_sel_hi:[1,0,1]
	v_pk_fma_f32 v[24:25], v[24:25], 0.5, v[46:47] op_sel_hi:[1,0,1]
	v_pk_fma_f32 v[34:35], v[18:19], 0.5, v[40:41] op_sel_hi:[1,0,1]
	v_pk_fma_f32 v[36:37], v[16:17], 0.5, v[50:51] op_sel_hi:[1,0,1]
	v_mul_f32_e32 v18, v29, v29
	v_mul_f32_e32 v19, v31, v31
	v_mul_f32_e32 v38, v21, v21
	v_mul_f32_e32 v39, v23, v23
	v_cvt_pk_bf16_f32 v16, v28, v29
	v_mul_f32_e32 v29, v25, v25
	v_mul_f32_e32 v40, v37, v37
	v_fmac_f32_e32 v18, v28, v28
	v_fmac_f32_e32 v19, v30, v30
	v_fmac_f32_e32 v38, v20, v20
	v_fmac_f32_e32 v39, v22, v22
	v_cvt_pk_bf16_f32 v17, v30, v31
	v_mul_f32_e32 v31, v27, v27
	v_mul_f32_e32 v41, v35, v35
	v_fmac_f32_e32 v29, v24, v24
	v_fmac_f32_e32 v40, v36, v36
	v_add_f32_e32 v18, v18, v19
	v_add_f32_e32 v19, v38, v39
	v_fmac_f32_e32 v31, v26, v26
	v_fmac_f32_e32 v41, v34, v34
	v_add_f32_e32 v18, v29, v18
	v_add_f32_e32 v19, v40, v19
	v_add_f32_e32 v18, v31, v18
	v_add_f32_e32 v19, v41, v19
	v_add_f32_e32 v28, v18, v19
	ds_bpermute_b32 v29, v156, v28
	v_cvt_pk_bf16_f32 v18, v24, v25
	v_cvt_pk_bf16_f32 v19, v26, v27
	global_store_dwordx4 v[42:43], v[16:19], off
	s_waitcnt lgkmcnt(0)
	s_nop 0
	v_add_f32_e32 v16, v28, v29
	ds_bpermute_b32 v17, v155, v16
	v_cvt_pk_bf16_f32 v18, v20, v21
	v_cvt_pk_bf16_f32 v19, v22, v23
	v_cvt_pk_bf16_f32 v20, v36, v37
	v_cvt_pk_bf16_f32 v21, v34, v35
	global_store_dwordx4 v[42:43], v[18:21], off offset:256
	s_and_saveexec_b64 s[26:27], s[4:5]
	s_cbranch_execz .LBB0_263
	v_lshlrev_b64 v[18:19], 6, v[32:33]
	v_lshl_add_u64 v[18:19], s[16:17], 0, v[18:19]
	v_lshl_add_u64 v[18:19], s[20:21], 2, v[18:19]
	s_lshl_b32 s12, s45, 2
	v_lshl_add_u64 v[18:19], v[18:19], 0, s[12:13]
	s_waitcnt lgkmcnt(0)
	v_add_f32_e32 v16, v16, v17
	global_store_dword v[18:19], v16, off
.LBB0_263:
	s_or_b64 exec, exec, s[26:27]
	v_add_u32_e32 v16, 0xb0, v146
	s_waitcnt lgkmcnt(0)
	v_ashrrev_i32_e32 v17, 31, v16
	v_lshlrev_b64 v[18:19], 11, v[16:17]
	v_lshl_add_u64 v[18:19], s[14:15], 0, v[18:19]
	v_lshl_add_u64 v[26:27], v[144:145], 1, v[18:19]
	s_waitcnt vmcnt(15)
	v_lshlrev_b32_e32 v28, 16, v224
	v_and_b32_e32 v29, 0xffff0000, v224
	v_lshlrev_b32_e32 v18, 16, v225
	v_and_b32_e32 v19, 0xffff0000, v225
	s_waitcnt vmcnt(14)
	v_lshlrev_b32_e32 v32, 16, v228
	v_and_b32_e32 v33, 0xffff0000, v228
	v_lshlrev_b32_e32 v22, 16, v229
	v_and_b32_e32 v23, 0xffff0000, v229
	v_lshlrev_b32_e32 v30, 16, v226
	v_and_b32_e32 v31, 0xffff0000, v226
	v_lshlrev_b32_e32 v20, 16, v227
	v_and_b32_e32 v21, 0xffff0000, v227
	v_lshlrev_b32_e32 v34, 16, v230
	v_and_b32_e32 v35, 0xffff0000, v230
	v_lshlrev_b32_e32 v24, 16, v231
	v_and_b32_e32 v25, 0xffff0000, v231
	v_pk_fma_f32 v[14:15], v[14:15], 0.5, v[18:19] op_sel_hi:[1,0,1]
	v_pk_fma_f32 v[12:13], v[12:13], 0.5, v[28:29] op_sel_hi:[1,0,1]
	v_pk_fma_f32 v[6:7], v[6:7], 0.5, v[22:23] op_sel_hi:[1,0,1]
	v_pk_fma_f32 v[4:5], v[4:5], 0.5, v[32:33] op_sel_hi:[1,0,1]
	v_pk_fma_f32 v[10:11], v[10:11], 0.5, v[20:21] op_sel_hi:[1,0,1]
	v_pk_fma_f32 v[8:9], v[8:9], 0.5, v[30:31] op_sel_hi:[1,0,1]
	v_pk_fma_f32 v[18:19], v[2:3], 0.5, v[24:25] op_sel_hi:[1,0,1]
	v_pk_fma_f32 v[20:21], v[0:1], 0.5, v[34:35] op_sel_hi:[1,0,1]
	v_mul_f32_e32 v2, v13, v13
	v_mul_f32_e32 v3, v15, v15
	v_mul_f32_e32 v22, v5, v5
	v_mul_f32_e32 v23, v7, v7
	v_cvt_pk_bf16_f32 v0, v12, v13
	v_mul_f32_e32 v13, v9, v9
	v_mul_f32_e32 v24, v21, v21
	v_fmac_f32_e32 v2, v12, v12
	v_fmac_f32_e32 v3, v14, v14
	v_fmac_f32_e32 v22, v4, v4
	v_fmac_f32_e32 v23, v6, v6
	v_cvt_pk_bf16_f32 v1, v14, v15
	v_mul_f32_e32 v15, v11, v11
	v_mul_f32_e32 v25, v19, v19
	v_fmac_f32_e32 v13, v8, v8
	v_fmac_f32_e32 v24, v20, v20
	v_add_f32_e32 v2, v2, v3
	v_add_f32_e32 v3, v22, v23
	v_fmac_f32_e32 v15, v10, v10
	v_fmac_f32_e32 v25, v18, v18
	v_add_f32_e32 v2, v13, v2
	v_add_f32_e32 v3, v24, v3
	v_add_f32_e32 v2, v15, v2
	v_add_f32_e32 v3, v25, v3
	v_add_f32_e32 v12, v2, v3
	ds_bpermute_b32 v13, v156, v12
	v_cvt_pk_bf16_f32 v2, v8, v9
	v_cvt_pk_bf16_f32 v3, v10, v11
	global_store_dwordx4 v[26:27], v[0:3], off
	s_waitcnt lgkmcnt(0)
	s_nop 0
	v_add_f32_e32 v0, v12, v13
	ds_bpermute_b32 v1, v155, v0
	v_cvt_pk_bf16_f32 v2, v4, v5
	v_cvt_pk_bf16_f32 v3, v6, v7
	v_cvt_pk_bf16_f32 v4, v20, v21
	v_cvt_pk_bf16_f32 v5, v18, v19
	global_store_dwordx4 v[26:27], v[2:5], off offset:256
	s_and_saveexec_b64 s[26:27], s[4:5]
	s_cbranch_execz .LBB0_240
	v_lshlrev_b64 v[2:3], 6, v[16:17]
	v_lshl_add_u64 v[2:3], s[16:17], 0, v[2:3]
	v_lshl_add_u64 v[2:3], s[20:21], 2, v[2:3]
	s_lshl_b32 s12, s45, 2
	v_lshl_add_u64 v[2:3], v[2:3], 0, s[12:13]
	s_waitcnt lgkmcnt(0)
	v_add_f32_e32 v0, v0, v1
	global_store_dword v[2:3], v0, off
	s_branch .LBB0_240

.Lg786_noy:
.LBB0_786:
	ds_read_b128 v[144:147], v151
	ds_read_b128 v[156:159], v151 offset:1024
	ds_read_b128 v[160:163], v151 offset:2048
	ds_read_b128 v[164:167], v151 offset:3072
	s_add_u32 s30, s28, 0xfffc0080
	s_addc_u32 s31, s29, -1
	s_cmp_eq_u32 s61, 12
	s_cselect_b32 s35, s19, s31
	s_cselect_b32 s34, s57, s30
	s_cselect_b32 s31, s17, s60
	s_cselect_b32 s30, s58, s59
	s_add_i32 m0, s45, 0xc000
	ds_read_b128 v[168:171], v152
	ds_read_b128 v[172:175], v152 offset:1024
	ds_read_b128 v[176:179], v152 offset:2048
	ds_read_b128 v[180:183], v152 offset:3072
	ds_read_b128 v[184:187], v152 offset:4096
	ds_read_b128 v[188:191], v152 offset:5120
	ds_read_b128 v[192:195], v152 offset:6144
	ds_read_b128 v[196:199], v152 offset:7168
	global_load_lds_dwordx4 v136, s[28:29]
	s_add_i32 m0, s45, 0xe000
	s_nop 0
	global_load_lds_dwordx4 v138, s[28:29]
	s_waitcnt lgkmcnt(8)
	s_barrier
	s_waitcnt lgkmcnt(0)
	s_setprio 1
	s_waitcnt lgkmcnt(0)
	v_mfma_f32_16x16x32_bf16 v[124:127], v[144:147], v[168:171], v[124:127]
	v_mfma_f32_16x16x32_bf16 v[120:123], v[160:163], v[168:171], v[120:123]
	v_mfma_f32_16x16x32_bf16 v[108:111], v[144:147], v[176:179], v[108:111]
	v_mfma_f32_16x16x32_bf16 v[104:107], v[160:163], v[176:179], v[104:107]
	v_mfma_f32_16x16x32_bf16 v[92:95], v[144:147], v[184:187], v[92:95]
	v_mfma_f32_16x16x32_bf16 v[88:91], v[160:163], v[184:187], v[88:91]
	v_mfma_f32_16x16x32_bf16 v[76:79], v[144:147], v[192:195], v[76:79]
	v_mfma_f32_16x16x32_bf16 v[72:75], v[160:163], v[192:195], v[72:75]
	v_mfma_f32_16x16x32_bf16 v[124:127], v[156:159], v[172:175], v[124:127]
	v_mfma_f32_16x16x32_bf16 v[120:123], v[164:167], v[172:175], v[120:123]
	v_mfma_f32_16x16x32_bf16 v[108:111], v[156:159], v[180:183], v[108:111]
	v_mfma_f32_16x16x32_bf16 v[104:107], v[164:167], v[180:183], v[104:107]
	v_mfma_f32_16x16x32_bf16 v[92:95], v[156:159], v[188:191], v[92:95]
	v_mfma_f32_16x16x32_bf16 v[88:91], v[164:167], v[188:191], v[88:91]
	v_mfma_f32_16x16x32_bf16 v[76:79], v[156:159], v[196:199], v[76:79]
	v_mfma_f32_16x16x32_bf16 v[72:75], v[164:167], v[196:199], v[72:75]
	s_setprio 0
	s_barrier
	s_add_i32 s62, s53, s42
	s_add_u32 s80, s30, 0x80
	s_addc_u32 s81, s31, 0
	s_mov_b32 m0, s62
	ds_read_b128 v[200:203], v153
	ds_read_b128 v[204:207], v153 offset:1024
	ds_read_b128 v[208:211], v153 offset:2048
	ds_read_b128 v[212:215], v153 offset:3072
	global_load_lds_dwordx4 v132, s[30:31]
	s_add_i32 m0, s62, 0x2000
	s_nop 0
	global_load_lds_dwordx4 v128, s[30:31]
	s_barrier
	s_waitcnt lgkmcnt(0)
	s_setprio 1
	s_waitcnt lgkmcnt(0)
	v_mfma_f32_16x16x32_bf16 v[116:119], v[200:203], v[168:171], v[116:119]
	v_mfma_f32_16x16x32_bf16 v[112:115], v[208:211], v[168:171], v[112:115]
	v_mfma_f32_16x16x32_bf16 v[100:103], v[200:203], v[176:179], v[100:103]
	v_mfma_f32_16x16x32_bf16 v[96:99], v[208:211], v[176:179], v[96:99]
	v_mfma_f32_16x16x32_bf16 v[84:87], v[200:203], v[184:187], v[84:87]
	v_mfma_f32_16x16x32_bf16 v[80:83], v[208:211], v[184:187], v[80:83]
	v_mfma_f32_16x16x32_bf16 v[68:71], v[200:203], v[192:195], v[68:71]
	v_mfma_f32_16x16x32_bf16 v[64:67], v[208:211], v[192:195], v[64:67]
	v_mfma_f32_16x16x32_bf16 v[116:119], v[204:207], v[172:175], v[116:119]
	v_mfma_f32_16x16x32_bf16 v[112:115], v[212:215], v[172:175], v[112:115]
	v_mfma_f32_16x16x32_bf16 v[100:103], v[204:207], v[180:183], v[100:103]
	v_mfma_f32_16x16x32_bf16 v[96:99], v[212:215], v[180:183], v[96:99]
	v_mfma_f32_16x16x32_bf16 v[84:87], v[204:207], v[188:191], v[84:87]
	v_mfma_f32_16x16x32_bf16 v[80:83], v[212:215], v[188:191], v[80:83]
	v_mfma_f32_16x16x32_bf16 v[68:71], v[204:207], v[196:199], v[68:71]
	v_mfma_f32_16x16x32_bf16 v[64:67], v[212:215], v[196:199], v[64:67]
	s_setprio 0
	s_mov_b32 m0, s45
	s_add_u32 s82, s34, 0x80
	s_addc_u32 s83, s35, 0
	s_barrier
	ds_read_b128 v[168:171], v152 offset:16384
	ds_read_b128 v[172:175], v152 offset:17408
	ds_read_b128 v[176:179], v152 offset:18432
	ds_read_b128 v[180:183], v152 offset:19456
	ds_read_b128 v[184:187], v152 offset:20480
	ds_read_b128 v[188:191], v152 offset:21504
	ds_read_b128 v[192:195], v152 offset:22528
	ds_read_b128 v[196:199], v152 offset:23552
	global_load_lds_dwordx4 v134, s[34:35]
	s_mov_b32 m0, s46
	s_nop 0
	global_load_lds_dwordx4 v130, s[34:35]
	s_barrier
	s_waitcnt lgkmcnt(0)
	s_setprio 1
	s_waitcnt lgkmcnt(0)
	v_mfma_f32_16x16x32_bf16 v[60:63], v[144:147], v[168:171], v[60:63]
	v_mfma_f32_16x16x32_bf16 v[56:59], v[160:163], v[168:171], v[56:59]
	v_mfma_f32_16x16x32_bf16 v[44:47], v[144:147], v[176:179], v[44:47]
	v_mfma_f32_16x16x32_bf16 v[40:43], v[160:163], v[176:179], v[40:43]
	v_mfma_f32_16x16x32_bf16 v[28:31], v[144:147], v[184:187], v[28:31]
	v_mfma_f32_16x16x32_bf16 v[24:27], v[160:163], v[184:187], v[24:27]
	v_mfma_f32_16x16x32_bf16 v[12:15], v[144:147], v[192:195], v[12:15]
	v_mfma_f32_16x16x32_bf16 v[8:11], v[160:163], v[192:195], v[8:11]
	v_mfma_f32_16x16x32_bf16 v[60:63], v[156:159], v[172:175], v[60:63]
	v_mfma_f32_16x16x32_bf16 v[56:59], v[164:167], v[172:175], v[56:59]
	v_mfma_f32_16x16x32_bf16 v[44:47], v[156:159], v[180:183], v[44:47]
	v_mfma_f32_16x16x32_bf16 v[40:43], v[164:167], v[180:183], v[40:43]
	v_mfma_f32_16x16x32_bf16 v[28:31], v[156:159], v[188:191], v[28:31]
	v_mfma_f32_16x16x32_bf16 v[24:27], v[164:167], v[188:191], v[24:27]
	v_mfma_f32_16x16x32_bf16 v[12:15], v[156:159], v[196:199], v[12:15]
	v_mfma_f32_16x16x32_bf16 v[8:11], v[164:167], v[196:199], v[8:11]
	s_setprio 0
	s_barrier
	s_add_u32 s62, s30, 0x40000
	s_addc_u32 s63, s31, 0
	s_add_i32 s64, s54, s42
	s_mov_b32 m0, s64
	s_nop 0
	global_load_lds_dwordx4 v132, s[62:63]
	s_add_i32 m0, s64, 0x2000
	s_nop 0
	global_load_lds_dwordx4 v128, s[62:63]
	s_waitcnt vmcnt(6)
	s_barrier
	s_setprio 1
	v_mfma_f32_16x16x32_bf16 v[52:55], v[200:203], v[168:171], v[52:55]
	v_mfma_f32_16x16x32_bf16 v[48:51], v[208:211], v[168:171], v[48:51]
	v_mfma_f32_16x16x32_bf16 v[36:39], v[200:203], v[176:179], v[36:39]
	v_mfma_f32_16x16x32_bf16 v[32:35], v[208:211], v[176:179], v[32:35]
	v_mfma_f32_16x16x32_bf16 v[20:23], v[200:203], v[184:187], v[20:23]
	v_mfma_f32_16x16x32_bf16 v[16:19], v[208:211], v[184:187], v[16:19]
	v_mfma_f32_16x16x32_bf16 v[4:7], v[200:203], v[192:195], v[4:7]
	v_mfma_f32_16x16x32_bf16 v[0:3], v[208:211], v[192:195], v[0:3]
	v_mfma_f32_16x16x32_bf16 v[52:55], v[204:207], v[172:175], v[52:55]
	v_mfma_f32_16x16x32_bf16 v[48:51], v[212:215], v[172:175], v[48:51]
	v_mfma_f32_16x16x32_bf16 v[36:39], v[204:207], v[180:183], v[36:39]
	v_mfma_f32_16x16x32_bf16 v[32:35], v[212:215], v[180:183], v[32:35]
	v_mfma_f32_16x16x32_bf16 v[20:23], v[204:207], v[188:191], v[20:23]
	v_mfma_f32_16x16x32_bf16 v[16:19], v[212:215], v[188:191], v[16:19]
	v_mfma_f32_16x16x32_bf16 v[4:7], v[204:207], v[196:199], v[4:7]
	v_mfma_f32_16x16x32_bf16 v[0:3], v[212:215], v[196:199], v[0:3]
	s_setprio 0
	s_add_i32 s62, 0, 0x18000
	v_add_u32_e32 v155, s62, v149
	s_barrier
	ds_read_b128 v[144:147], v155
	ds_read_b128 v[156:159], v155 offset:1024
	ds_read_b128 v[160:163], v155 offset:2048
	ds_read_b128 v[164:167], v155 offset:3072
	s_add_u32 s34, s34, 0x40000
	s_addc_u32 s35, s35, 0
	s_mov_b32 m0, s47
	ds_read_b128 v[168:171], v152 offset:32768
	ds_read_b128 v[172:175], v152 offset:33792
	ds_read_b128 v[176:179], v152 offset:34816
	ds_read_b128 v[180:183], v152 offset:35840
	ds_read_b128 v[184:187], v152 offset:36864
	ds_read_b128 v[188:191], v152 offset:37888
	ds_read_b128 v[192:195], v152 offset:38912
	ds_read_b128 v[196:199], v152 offset:39936
	global_load_lds_dwordx4 v134, s[34:35]
	s_mov_b32 m0, s48
	s_nop 0
	global_load_lds_dwordx4 v130, s[34:35]
	s_waitcnt lgkmcnt(8)
	s_barrier
	s_waitcnt lgkmcnt(0)
	s_setprio 1
	s_waitcnt lgkmcnt(0)
	v_mfma_f32_16x16x32_bf16 v[124:127], v[144:147], v[168:171], v[124:127]
	v_mfma_f32_16x16x32_bf16 v[120:123], v[160:163], v[168:171], v[120:123]
	v_mfma_f32_16x16x32_bf16 v[108:111], v[144:147], v[176:179], v[108:111]
	v_mfma_f32_16x16x32_bf16 v[104:107], v[160:163], v[176:179], v[104:107]
	v_mfma_f32_16x16x32_bf16 v[92:95], v[144:147], v[184:187], v[92:95]
	v_mfma_f32_16x16x32_bf16 v[88:91], v[160:163], v[184:187], v[88:91]
	v_mfma_f32_16x16x32_bf16 v[76:79], v[144:147], v[192:195], v[76:79]
	v_mfma_f32_16x16x32_bf16 v[72:75], v[160:163], v[192:195], v[72:75]
	v_mfma_f32_16x16x32_bf16 v[124:127], v[156:159], v[172:175], v[124:127]
	v_mfma_f32_16x16x32_bf16 v[120:123], v[164:167], v[172:175], v[120:123]
	v_mfma_f32_16x16x32_bf16 v[108:111], v[156:159], v[180:183], v[108:111]
	v_mfma_f32_16x16x32_bf16 v[104:107], v[164:167], v[180:183], v[104:107]
	v_mfma_f32_16x16x32_bf16 v[92:95], v[156:159], v[188:191], v[92:95]
	v_mfma_f32_16x16x32_bf16 v[88:91], v[164:167], v[188:191], v[88:91]
	v_mfma_f32_16x16x32_bf16 v[76:79], v[156:159], v[196:199], v[76:79]
	v_mfma_f32_16x16x32_bf16 v[72:75], v[164:167], v[196:199], v[72:75]
	s_setprio 0
	s_barrier
	s_add_i32 s34, 0, 0x1c000
	s_add_i32 s35, s62, s42
	v_add_u32_e32 v155, s34, v149
	s_mov_b32 m0, s35
	ds_read_b128 v[200:203], v155
	ds_read_b128 v[204:207], v155 offset:1024
	ds_read_b128 v[208:211], v155 offset:2048
	ds_read_b128 v[212:215], v155 offset:3072
	global_load_lds_dwordx4 v132, s[80:81]
	s_add_i32 m0, s35, 0x2000
	s_nop 0
	global_load_lds_dwordx4 v128, s[80:81]
	s_barrier
	s_waitcnt lgkmcnt(0)
	s_setprio 1
	s_waitcnt lgkmcnt(0)
	v_mfma_f32_16x16x32_bf16 v[116:119], v[200:203], v[168:171], v[116:119]
	v_mfma_f32_16x16x32_bf16 v[112:115], v[208:211], v[168:171], v[112:115]
	v_mfma_f32_16x16x32_bf16 v[100:103], v[200:203], v[176:179], v[100:103]
	v_mfma_f32_16x16x32_bf16 v[96:99], v[208:211], v[176:179], v[96:99]
	v_mfma_f32_16x16x32_bf16 v[84:87], v[200:203], v[184:187], v[84:87]
	v_mfma_f32_16x16x32_bf16 v[80:83], v[208:211], v[184:187], v[80:83]
	v_mfma_f32_16x16x32_bf16 v[68:71], v[200:203], v[192:195], v[68:71]
	v_mfma_f32_16x16x32_bf16 v[64:67], v[208:211], v[192:195], v[64:67]
	v_mfma_f32_16x16x32_bf16 v[116:119], v[204:207], v[172:175], v[116:119]
	v_mfma_f32_16x16x32_bf16 v[112:115], v[212:215], v[172:175], v[112:115]
	v_mfma_f32_16x16x32_bf16 v[100:103], v[204:207], v[180:183], v[100:103]
	v_mfma_f32_16x16x32_bf16 v[96:99], v[212:215], v[180:183], v[96:99]
	v_mfma_f32_16x16x32_bf16 v[84:87], v[204:207], v[188:191], v[84:87]
	v_mfma_f32_16x16x32_bf16 v[80:83], v[212:215], v[188:191], v[80:83]
	v_mfma_f32_16x16x32_bf16 v[68:71], v[204:207], v[196:199], v[68:71]
	v_mfma_f32_16x16x32_bf16 v[64:67], v[212:215], v[196:199], v[64:67]
	s_setprio 0
	s_mov_b32 m0, s50
	s_barrier
	ds_read_b128 v[168:171], v152 offset:49152
	ds_read_b128 v[172:175], v152 offset:50176
	ds_read_b128 v[176:179], v152 offset:51200
	ds_read_b128 v[180:183], v152 offset:52224
	ds_read_b128 v[184:187], v152 offset:53248
	ds_read_b128 v[188:191], v152 offset:54272
	ds_read_b128 v[192:195], v152 offset:55296
	ds_read_b128 v[196:199], v152 offset:56320
	global_load_lds_dwordx4 v134, s[82:83]
	s_mov_b32 m0, s51
	s_nop 0
	global_load_lds_dwordx4 v130, s[82:83]
	s_barrier
	s_waitcnt lgkmcnt(0)
	s_setprio 1
	s_waitcnt lgkmcnt(0)
	v_mfma_f32_16x16x32_bf16 v[60:63], v[144:147], v[168:171], v[60:63]
	v_mfma_f32_16x16x32_bf16 v[56:59], v[160:163], v[168:171], v[56:59]
	v_mfma_f32_16x16x32_bf16 v[44:47], v[144:147], v[176:179], v[44:47]
	v_mfma_f32_16x16x32_bf16 v[40:43], v[160:163], v[176:179], v[40:43]
	v_mfma_f32_16x16x32_bf16 v[28:31], v[144:147], v[184:187], v[28:31]
	v_mfma_f32_16x16x32_bf16 v[24:27], v[160:163], v[184:187], v[24:27]
	v_mfma_f32_16x16x32_bf16 v[12:15], v[144:147], v[192:195], v[12:15]
	v_mfma_f32_16x16x32_bf16 v[8:11], v[160:163], v[192:195], v[8:11]
	v_mfma_f32_16x16x32_bf16 v[60:63], v[156:159], v[172:175], v[60:63]
	v_mfma_f32_16x16x32_bf16 v[56:59], v[164:167], v[172:175], v[56:59]
	v_mfma_f32_16x16x32_bf16 v[44:47], v[156:159], v[180:183], v[44:47]
	v_mfma_f32_16x16x32_bf16 v[40:43], v[164:167], v[180:183], v[40:43]
	v_mfma_f32_16x16x32_bf16 v[28:31], v[156:159], v[188:191], v[28:31]
	v_mfma_f32_16x16x32_bf16 v[24:27], v[164:167], v[188:191], v[24:27]
	v_mfma_f32_16x16x32_bf16 v[12:15], v[156:159], v[196:199], v[12:15]
	v_mfma_f32_16x16x32_bf16 v[8:11], v[164:167], v[196:199], v[8:11]
	s_setprio 0
	s_barrier
	s_add_u32 s30, s30, 0x40080
	s_addc_u32 s31, s31, 0
	s_add_i32 s34, s34, s42
	s_mov_b32 m0, s34
	s_nop 0
	global_load_lds_dwordx4 v132, s[30:31]
	s_add_i32 m0, s34, 0x2000
	s_nop 0
	global_load_lds_dwordx4 v128, s[30:31]
	s_waitcnt vmcnt(6)
	s_barrier
	s_setprio 1
	v_mfma_f32_16x16x32_bf16 v[52:55], v[200:203], v[168:171], v[52:55]
	v_mfma_f32_16x16x32_bf16 v[48:51], v[208:211], v[168:171], v[48:51]
	v_mfma_f32_16x16x32_bf16 v[36:39], v[200:203], v[176:179], v[36:39]
	v_mfma_f32_16x16x32_bf16 v[32:35], v[208:211], v[176:179], v[32:35]
	v_mfma_f32_16x16x32_bf16 v[20:23], v[200:203], v[184:187], v[20:23]
	v_mfma_f32_16x16x32_bf16 v[16:19], v[208:211], v[184:187], v[16:19]
	v_mfma_f32_16x16x32_bf16 v[4:7], v[200:203], v[192:195], v[4:7]
	v_mfma_f32_16x16x32_bf16 v[0:3], v[208:211], v[192:195], v[0:3]
	v_mfma_f32_16x16x32_bf16 v[52:55], v[204:207], v[172:175], v[52:55]
	v_mfma_f32_16x16x32_bf16 v[48:51], v[212:215], v[172:175], v[48:51]
	v_mfma_f32_16x16x32_bf16 v[36:39], v[204:207], v[180:183], v[36:39]
	v_mfma_f32_16x16x32_bf16 v[32:35], v[212:215], v[180:183], v[32:35]
	v_mfma_f32_16x16x32_bf16 v[20:23], v[204:207], v[188:191], v[20:23]
	v_mfma_f32_16x16x32_bf16 v[16:19], v[212:215], v[188:191], v[16:19]
	v_mfma_f32_16x16x32_bf16 v[4:7], v[204:207], v[196:199], v[4:7]
	v_mfma_f32_16x16x32_bf16 v[0:3], v[212:215], v[196:199], v[0:3]
	s_setprio 0
	s_add_i32 s61, s61, 2
	s_add_u32 s28, s28, 0x100
	s_addc_u32 s29, s29, 0
	s_add_u32 s59, s59, 0x100
	s_addc_u32 s60, s60, 0
	s_cmp_gt_u32 s61, 13
	s_barrier
	s_cbranch_scc0 .LBB0_786
	v_lshl_add_u32 v146, s8, 8, v148
	v_ashrrev_i32_e32 v147, 31, v146
	v_lshl_or_b32 v144, s56, 8, v150
	v_lshlrev_b64 v[156:157], 11, v[146:147]
	v_ashrrev_i32_e32 v145, 31, v144
	v_lshl_add_u64 v[156:157], s[10:11], 0, v[156:157]
	v_lshl_add_u64 v[166:167], v[144:145], 1, v[156:157]
	global_load_dwordx4 v[158:161], v[166:167], off
	global_load_dwordx4 v[162:165], v[166:167], off offset:256
	s_mov_b64 s[84:85], 0x8000
	s_mov_b64 s[86:87], 0x28000
	v_lshl_add_u64 v[232:233], v[166:167], 0, s[84:85]
	global_load_dwordx4 v[176:179], v[232:233], off
	global_load_dwordx4 v[180:183], v[232:233], off offset:256
	v_lshl_add_u64 v[232:233], v[232:233], 0, s[84:85]
	global_load_dwordx4 v[184:187], v[232:233], off
	global_load_dwordx4 v[188:191], v[232:233], off offset:256
	v_lshl_add_u64 v[232:233], v[232:233], 0, s[84:85]
	global_load_dwordx4 v[192:195], v[232:233], off
	global_load_dwordx4 v[196:199], v[232:233], off offset:256
	v_lshl_add_u64 v[232:233], v[232:233], 0, s[86:87]
	global_load_dwordx4 v[200:203], v[232:233], off
	global_load_dwordx4 v[204:207], v[232:233], off offset:256
	v_lshl_add_u64 v[232:233], v[232:233], 0, s[84:85]
	global_load_dwordx4 v[208:211], v[232:233], off
	global_load_dwordx4 v[212:215], v[232:233], off offset:256
	v_lshl_add_u64 v[232:233], v[232:233], 0, s[84:85]
	global_load_dwordx4 v[216:219], v[232:233], off
	global_load_dwordx4 v[220:223], v[232:233], off offset:256
	v_lshl_add_u64 v[232:233], v[232:233], 0, s[84:85]
	global_load_dwordx4 v[224:227], v[232:233], off
	global_load_dwordx4 v[228:231], v[232:233], off offset:256
	s_cmpk_gt_u32 s37, 0xff
	s_cbranch_scc1 .Lg786_nox
	s_barrier
.Lg786_nox:
	v_and_b32_e32 v156, 64, v154
	v_xor_b32_e32 v155, 16, v154
	v_add_u32_e32 v156, 64, v156
	v_xor_b32_e32 v157, 32, v154
	v_cmp_lt_i32_e32 vcc, v155, v156
	s_lshl_b32 s28, s56, 2
	s_ashr_i32 s29, s28, 31
	v_cndmask_b32_e32 v155, v154, v155, vcc
	v_cmp_lt_i32_e32 vcc, v157, v156
	v_lshlrev_b32_e32 v156, 2, v155
	s_waitcnt vmcnt(14)
	v_lshlrev_b32_e32 v168, 16, v158
	v_and_b32_e32 v169, 0xffff0000, v158
	v_lshlrev_b32_e32 v158, 16, v159
	v_and_b32_e32 v159, 0xffff0000, v159
	v_lshlrev_b32_e32 v172, 16, v162
	v_and_b32_e32 v173, 0xffff0000, v162
	v_lshlrev_b32_e32 v162, 16, v163
	v_and_b32_e32 v163, 0xffff0000, v163
	v_cndmask_b32_e32 v157, v154, v157, vcc
	v_lshlrev_b32_e32 v170, 16, v160
	v_and_b32_e32 v171, 0xffff0000, v160
	v_lshlrev_b32_e32 v160, 16, v161
	v_and_b32_e32 v161, 0xffff0000, v161
	v_lshlrev_b32_e32 v174, 16, v164
	v_and_b32_e32 v175, 0xffff0000, v164
	v_lshlrev_b32_e32 v164, 16, v165
	v_and_b32_e32 v165, 0xffff0000, v165
	v_pk_add_f32 v[126:127], v[126:127], v[158:159]
	v_pk_add_f32 v[124:125], v[124:125], v[168:169]
	v_pk_add_f32 v[118:119], v[118:119], v[162:163]
	v_pk_add_f32 v[116:117], v[116:117], v[172:173]
	v_lshlrev_b32_e32 v155, 2, v157
	v_pk_add_f32 v[122:123], v[122:123], v[160:161]
	v_pk_add_f32 v[120:121], v[120:121], v[170:171]
	v_pk_add_f32 v[158:159], v[114:115], v[164:165]
	v_pk_add_f32 v[160:161], v[112:113], v[174:175]
	v_mul_f32_e32 v114, v125, v125
	v_mul_f32_e32 v115, v127, v127
	v_mul_f32_e32 v157, v117, v117
	v_mul_f32_e32 v162, v119, v119
	v_cvt_pk_bf16_f32 v112, v124, v125
	v_mul_f32_e32 v125, v121, v121
	v_mul_f32_e32 v163, v161, v161
	v_fmac_f32_e32 v114, v124, v124
	v_fmac_f32_e32 v115, v126, v126
	v_fmac_f32_e32 v157, v116, v116
	v_fmac_f32_e32 v162, v118, v118
	v_cvt_pk_bf16_f32 v113, v126, v127
	v_mul_f32_e32 v127, v123, v123
	v_mul_f32_e32 v164, v159, v159
	v_fmac_f32_e32 v125, v120, v120
	v_fmac_f32_e32 v163, v160, v160
	v_add_f32_e32 v114, v114, v115
	v_add_f32_e32 v115, v157, v162
	v_fmac_f32_e32 v127, v122, v122
	v_fmac_f32_e32 v164, v158, v158
	v_add_f32_e32 v114, v125, v114
	v_add_f32_e32 v115, v163, v115
	v_add_f32_e32 v114, v127, v114
	v_add_f32_e32 v115, v164, v115
	v_add_f32_e32 v124, v114, v115
	ds_bpermute_b32 v125, v156, v124
	v_cvt_pk_bf16_f32 v114, v120, v121
	v_cvt_pk_bf16_f32 v115, v122, v123
	global_store_dwordx4 v[166:167], v[112:115], off
	s_waitcnt lgkmcnt(0)
	s_nop 0
	v_add_f32_e32 v112, v124, v125
	ds_bpermute_b32 v113, v155, v112
	v_cvt_pk_bf16_f32 v114, v116, v117
	v_cvt_pk_bf16_f32 v115, v118, v119
	v_cvt_pk_bf16_f32 v116, v160, v161
	v_cvt_pk_bf16_f32 v117, v158, v159
	global_store_dwordx4 v[166:167], v[114:117], off offset:256
	s_and_saveexec_b64 s[30:31], s[4:5]
	s_cbranch_execz .LBB0_789
	v_lshlrev_b64 v[114:115], 6, v[146:147]
	v_lshl_add_u64 v[114:115], s[12:13], 0, v[114:115]
	v_lshl_add_u64 v[114:115], s[28:29], 2, v[114:115]
	s_lshl_b32 s8, s49, 2
	v_lshl_add_u64 v[114:115], v[114:115], 0, s[8:9]
	s_waitcnt lgkmcnt(0)
	v_add_f32_e32 v112, v112, v113
	global_store_dword v[114:115], v112, off
.LBB0_789:
	s_or_b64 exec, exec, s[30:31]
	v_or_b32_e32 v112, 16, v146
	s_waitcnt lgkmcnt(0)
	v_ashrrev_i32_e32 v113, 31, v112
	v_lshlrev_b64 v[114:115], 11, v[112:113]
	v_lshl_add_u64 v[114:115], s[10:11], 0, v[114:115]
	v_lshl_add_u64 v[122:123], v[144:145], 1, v[114:115]
	s_waitcnt vmcnt(15)
	v_lshlrev_b32_e32 v124, 16, v176
	v_and_b32_e32 v125, 0xffff0000, v176
	v_lshlrev_b32_e32 v114, 16, v177
	v_and_b32_e32 v115, 0xffff0000, v177
	s_waitcnt vmcnt(14)
	v_lshlrev_b32_e32 v158, 16, v180
	v_and_b32_e32 v159, 0xffff0000, v180
	v_lshlrev_b32_e32 v118, 16, v181
	v_and_b32_e32 v119, 0xffff0000, v181
	v_lshlrev_b32_e32 v126, 16, v178
	v_and_b32_e32 v127, 0xffff0000, v178
	v_lshlrev_b32_e32 v116, 16, v179
	v_and_b32_e32 v117, 0xffff0000, v179
	v_lshlrev_b32_e32 v160, 16, v182
	v_and_b32_e32 v161, 0xffff0000, v182
	v_lshlrev_b32_e32 v120, 16, v183
	v_and_b32_e32 v121, 0xffff0000, v183
	v_pk_add_f32 v[110:111], v[110:111], v[114:115]
	v_pk_add_f32 v[108:109], v[108:109], v[124:125]
	v_pk_add_f32 v[102:103], v[102:103], v[118:119]
	v_pk_add_f32 v[100:101], v[100:101], v[158:159]
	v_pk_add_f32 v[106:107], v[106:107], v[116:117]
	v_pk_add_f32 v[104:105], v[104:105], v[126:127]
	v_pk_add_f32 v[114:115], v[98:99], v[120:121]
	v_pk_add_f32 v[116:117], v[96:97], v[160:161]
	v_mul_f32_e32 v98, v109, v109
	v_mul_f32_e32 v99, v111, v111
	v_mul_f32_e32 v118, v101, v101
	v_mul_f32_e32 v119, v103, v103
	v_cvt_pk_bf16_f32 v96, v108, v109
	v_mul_f32_e32 v109, v105, v105
	v_mul_f32_e32 v120, v117, v117
	v_fmac_f32_e32 v98, v108, v108
	v_fmac_f32_e32 v99, v110, v110
	v_fmac_f32_e32 v118, v100, v100
	v_fmac_f32_e32 v119, v102, v102
	v_cvt_pk_bf16_f32 v97, v110, v111
	v_mul_f32_e32 v111, v107, v107
	v_mul_f32_e32 v121, v115, v115
	v_fmac_f32_e32 v109, v104, v104
	v_fmac_f32_e32 v120, v116, v116
	v_add_f32_e32 v98, v98, v99
	v_add_f32_e32 v99, v118, v119
	v_fmac_f32_e32 v111, v106, v106
	v_fmac_f32_e32 v121, v114, v114
	v_add_f32_e32 v98, v109, v98
	v_add_f32_e32 v99, v120, v99
	v_add_f32_e32 v98, v111, v98
	v_add_f32_e32 v99, v121, v99
	v_add_f32_e32 v108, v98, v99
	ds_bpermute_b32 v109, v156, v108
	v_cvt_pk_bf16_f32 v98, v104, v105
	v_cvt_pk_bf16_f32 v99, v106, v107
	global_store_dwordx4 v[122:123], v[96:99], off
	s_waitcnt lgkmcnt(0)
	s_nop 0
	v_add_f32_e32 v96, v108, v109
	ds_bpermute_b32 v97, v155, v96
	v_cvt_pk_bf16_f32 v98, v100, v101
	v_cvt_pk_bf16_f32 v99, v102, v103
	v_cvt_pk_bf16_f32 v100, v116, v117
	v_cvt_pk_bf16_f32 v101, v114, v115
	global_store_dwordx4 v[122:123], v[98:101], off offset:256
	s_and_saveexec_b64 s[30:31], s[4:5]
	s_cbranch_execz .LBB0_791
	v_lshlrev_b64 v[98:99], 6, v[112:113]
	v_lshl_add_u64 v[98:99], s[12:13], 0, v[98:99]
	v_lshl_add_u64 v[98:99], s[28:29], 2, v[98:99]
	s_lshl_b32 s8, s49, 2
	v_lshl_add_u64 v[98:99], v[98:99], 0, s[8:9]
	s_waitcnt lgkmcnt(0)
	v_add_f32_e32 v96, v96, v97
	global_store_dword v[98:99], v96, off
.LBB0_791:
	s_or_b64 exec, exec, s[30:31]
	v_or_b32_e32 v96, 32, v146
	s_waitcnt lgkmcnt(0)
	v_ashrrev_i32_e32 v97, 31, v96
	v_lshlrev_b64 v[98:99], 11, v[96:97]
	v_lshl_add_u64 v[98:99], s[10:11], 0, v[98:99]
	v_lshl_add_u64 v[106:107], v[144:145], 1, v[98:99]
	s_waitcnt vmcnt(15)
	v_lshlrev_b32_e32 v108, 16, v184
	v_and_b32_e32 v109, 0xffff0000, v184
	v_lshlrev_b32_e32 v98, 16, v185
	v_and_b32_e32 v99, 0xffff0000, v185
	s_waitcnt vmcnt(14)
	v_lshlrev_b32_e32 v112, 16, v188
	v_and_b32_e32 v113, 0xffff0000, v188
	v_lshlrev_b32_e32 v102, 16, v189
	v_and_b32_e32 v103, 0xffff0000, v189
	v_lshlrev_b32_e32 v110, 16, v186
	v_and_b32_e32 v111, 0xffff0000, v186
	v_lshlrev_b32_e32 v100, 16, v187
	v_and_b32_e32 v101, 0xffff0000, v187
	v_lshlrev_b32_e32 v114, 16, v190
	v_and_b32_e32 v115, 0xffff0000, v190
	v_lshlrev_b32_e32 v104, 16, v191
	v_and_b32_e32 v105, 0xffff0000, v191
	v_pk_add_f32 v[94:95], v[94:95], v[98:99]
	v_pk_add_f32 v[92:93], v[92:93], v[108:109]
	v_pk_add_f32 v[86:87], v[86:87], v[102:103]
	v_pk_add_f32 v[84:85], v[84:85], v[112:113]
	v_pk_add_f32 v[90:91], v[90:91], v[100:101]
	v_pk_add_f32 v[88:89], v[88:89], v[110:111]
	v_pk_add_f32 v[98:99], v[82:83], v[104:105]
	v_pk_add_f32 v[100:101], v[80:81], v[114:115]
	v_mul_f32_e32 v82, v93, v93
	v_mul_f32_e32 v83, v95, v95
	v_mul_f32_e32 v102, v85, v85
	v_mul_f32_e32 v103, v87, v87
	v_cvt_pk_bf16_f32 v80, v92, v93
	v_mul_f32_e32 v93, v89, v89
	v_mul_f32_e32 v104, v101, v101
	v_fmac_f32_e32 v82, v92, v92
	v_fmac_f32_e32 v83, v94, v94
	v_fmac_f32_e32 v102, v84, v84
	v_fmac_f32_e32 v103, v86, v86
	v_cvt_pk_bf16_f32 v81, v94, v95
	v_mul_f32_e32 v95, v91, v91
	v_mul_f32_e32 v105, v99, v99
	v_fmac_f32_e32 v93, v88, v88
	v_fmac_f32_e32 v104, v100, v100
	v_add_f32_e32 v82, v82, v83
	v_add_f32_e32 v83, v102, v103
	v_fmac_f32_e32 v95, v90, v90
	v_fmac_f32_e32 v105, v98, v98
	v_add_f32_e32 v82, v93, v82
	v_add_f32_e32 v83, v104, v83
	v_add_f32_e32 v82, v95, v82
	v_add_f32_e32 v83, v105, v83
	v_add_f32_e32 v92, v82, v83
	ds_bpermute_b32 v93, v156, v92
	v_cvt_pk_bf16_f32 v82, v88, v89
	v_cvt_pk_bf16_f32 v83, v90, v91
	global_store_dwordx4 v[106:107], v[80:83], off
	s_waitcnt lgkmcnt(0)
	s_nop 0
	v_add_f32_e32 v80, v92, v93
	ds_bpermute_b32 v81, v155, v80
	v_cvt_pk_bf16_f32 v82, v84, v85
	v_cvt_pk_bf16_f32 v83, v86, v87
	v_cvt_pk_bf16_f32 v84, v100, v101
	v_cvt_pk_bf16_f32 v85, v98, v99
	global_store_dwordx4 v[106:107], v[82:85], off offset:256
	s_and_saveexec_b64 s[30:31], s[4:5]
	s_cbranch_execz .LBB0_793
	v_lshlrev_b64 v[82:83], 6, v[96:97]
	v_lshl_add_u64 v[82:83], s[12:13], 0, v[82:83]
	v_lshl_add_u64 v[82:83], s[28:29], 2, v[82:83]
	s_lshl_b32 s8, s49, 2
	v_lshl_add_u64 v[82:83], v[82:83], 0, s[8:9]
	s_waitcnt lgkmcnt(0)
	v_add_f32_e32 v80, v80, v81
	global_store_dword v[82:83], v80, off
.LBB0_793:
	s_or_b64 exec, exec, s[30:31]
	v_or_b32_e32 v80, 48, v146
	s_waitcnt lgkmcnt(0)
	v_ashrrev_i32_e32 v81, 31, v80
	v_lshlrev_b64 v[82:83], 11, v[80:81]
	v_lshl_add_u64 v[82:83], s[10:11], 0, v[82:83]
	v_lshl_add_u64 v[90:91], v[144:145], 1, v[82:83]
	s_waitcnt vmcnt(15)
	v_lshlrev_b32_e32 v92, 16, v192
	v_and_b32_e32 v93, 0xffff0000, v192
	v_lshlrev_b32_e32 v82, 16, v193
	v_and_b32_e32 v83, 0xffff0000, v193
	s_waitcnt vmcnt(14)
	v_lshlrev_b32_e32 v96, 16, v196
	v_and_b32_e32 v97, 0xffff0000, v196
	v_lshlrev_b32_e32 v86, 16, v197
	v_and_b32_e32 v87, 0xffff0000, v197
	v_lshlrev_b32_e32 v94, 16, v194
	v_and_b32_e32 v95, 0xffff0000, v194
	v_lshlrev_b32_e32 v84, 16, v195
	v_and_b32_e32 v85, 0xffff0000, v195
	v_lshlrev_b32_e32 v98, 16, v198
	v_and_b32_e32 v99, 0xffff0000, v198
	v_lshlrev_b32_e32 v88, 16, v199
	v_and_b32_e32 v89, 0xffff0000, v199
	v_pk_add_f32 v[78:79], v[78:79], v[82:83]
	v_pk_add_f32 v[76:77], v[76:77], v[92:93]
	v_pk_add_f32 v[70:71], v[70:71], v[86:87]
	v_pk_add_f32 v[68:69], v[68:69], v[96:97]
	v_pk_add_f32 v[74:75], v[74:75], v[84:85]
	v_pk_add_f32 v[72:73], v[72:73], v[94:95]
	v_pk_add_f32 v[82:83], v[66:67], v[88:89]
	v_pk_add_f32 v[84:85], v[64:65], v[98:99]
	v_mul_f32_e32 v66, v77, v77
	v_mul_f32_e32 v67, v79, v79
	v_mul_f32_e32 v86, v69, v69
	v_mul_f32_e32 v87, v71, v71
	v_cvt_pk_bf16_f32 v64, v76, v77
	v_mul_f32_e32 v77, v73, v73
	v_mul_f32_e32 v88, v85, v85
	v_fmac_f32_e32 v66, v76, v76
	v_fmac_f32_e32 v67, v78, v78
	v_fmac_f32_e32 v86, v68, v68
	v_fmac_f32_e32 v87, v70, v70
	v_cvt_pk_bf16_f32 v65, v78, v79
	v_mul_f32_e32 v79, v75, v75
	v_mul_f32_e32 v89, v83, v83
	v_fmac_f32_e32 v77, v72, v72
	v_fmac_f32_e32 v88, v84, v84
	v_add_f32_e32 v66, v66, v67
	v_add_f32_e32 v67, v86, v87
	v_fmac_f32_e32 v79, v74, v74
	v_fmac_f32_e32 v89, v82, v82
	v_add_f32_e32 v66, v77, v66
	v_add_f32_e32 v67, v88, v67
	v_add_f32_e32 v66, v79, v66
	v_add_f32_e32 v67, v89, v67
	v_add_f32_e32 v76, v66, v67
	ds_bpermute_b32 v77, v156, v76
	v_cvt_pk_bf16_f32 v66, v72, v73
	v_cvt_pk_bf16_f32 v67, v74, v75
	global_store_dwordx4 v[90:91], v[64:67], off
	s_waitcnt lgkmcnt(0)
	s_nop 0
	v_add_f32_e32 v64, v76, v77
	ds_bpermute_b32 v65, v155, v64
	v_cvt_pk_bf16_f32 v66, v68, v69
	v_cvt_pk_bf16_f32 v67, v70, v71
	v_cvt_pk_bf16_f32 v68, v84, v85
	v_cvt_pk_bf16_f32 v69, v82, v83
	global_store_dwordx4 v[90:91], v[66:69], off offset:256
	s_and_saveexec_b64 s[30:31], s[4:5]
	s_cbranch_execz .LBB0_795
	v_lshlrev_b64 v[66:67], 6, v[80:81]
	v_lshl_add_u64 v[66:67], s[12:13], 0, v[66:67]
	v_lshl_add_u64 v[66:67], s[28:29], 2, v[66:67]
	s_lshl_b32 s8, s49, 2
	v_lshl_add_u64 v[66:67], v[66:67], 0, s[8:9]
	s_waitcnt lgkmcnt(0)
	v_add_f32_e32 v64, v64, v65
	global_store_dword v[66:67], v64, off
.LBB0_795:
	s_or_b64 exec, exec, s[30:31]
	v_add_u32_e32 v64, 0x80, v146
	s_waitcnt lgkmcnt(0)
	v_ashrrev_i32_e32 v65, 31, v64
	v_lshlrev_b64 v[66:67], 11, v[64:65]
	v_lshl_add_u64 v[66:67], s[10:11], 0, v[66:67]
	v_lshl_add_u64 v[74:75], v[144:145], 1, v[66:67]
	s_waitcnt vmcnt(15)
	v_lshlrev_b32_e32 v76, 16, v200
	v_and_b32_e32 v77, 0xffff0000, v200
	v_lshlrev_b32_e32 v66, 16, v201
	v_and_b32_e32 v67, 0xffff0000, v201
	s_waitcnt vmcnt(14)
	v_lshlrev_b32_e32 v80, 16, v204
	v_and_b32_e32 v81, 0xffff0000, v204
	v_lshlrev_b32_e32 v70, 16, v205
	v_and_b32_e32 v71, 0xffff0000, v205
	v_lshlrev_b32_e32 v78, 16, v202
	v_and_b32_e32 v79, 0xffff0000, v202
	v_lshlrev_b32_e32 v68, 16, v203
	v_and_b32_e32 v69, 0xffff0000, v203
	v_lshlrev_b32_e32 v82, 16, v206
	v_and_b32_e32 v83, 0xffff0000, v206
	v_lshlrev_b32_e32 v72, 16, v207
	v_and_b32_e32 v73, 0xffff0000, v207
	v_pk_add_f32 v[62:63], v[62:63], v[66:67]
	v_pk_add_f32 v[60:61], v[60:61], v[76:77]
	v_pk_add_f32 v[54:55], v[54:55], v[70:71]
	v_pk_add_f32 v[52:53], v[52:53], v[80:81]
	v_pk_add_f32 v[58:59], v[58:59], v[68:69]
	v_pk_add_f32 v[56:57], v[56:57], v[78:79]
	v_pk_add_f32 v[66:67], v[50:51], v[72:73]
	v_pk_add_f32 v[68:69], v[48:49], v[82:83]
	v_mul_f32_e32 v50, v61, v61
	v_mul_f32_e32 v51, v63, v63
	v_mul_f32_e32 v70, v53, v53
	v_mul_f32_e32 v71, v55, v55
	v_cvt_pk_bf16_f32 v48, v60, v61
	v_mul_f32_e32 v61, v57, v57
	v_mul_f32_e32 v72, v69, v69
	v_fmac_f32_e32 v50, v60, v60
	v_fmac_f32_e32 v51, v62, v62
	v_fmac_f32_e32 v70, v52, v52
	v_fmac_f32_e32 v71, v54, v54
	v_cvt_pk_bf16_f32 v49, v62, v63
	v_mul_f32_e32 v63, v59, v59
	v_mul_f32_e32 v73, v67, v67
	v_fmac_f32_e32 v61, v56, v56
	v_fmac_f32_e32 v72, v68, v68
	v_add_f32_e32 v50, v50, v51
	v_add_f32_e32 v51, v70, v71
	v_fmac_f32_e32 v63, v58, v58
	v_fmac_f32_e32 v73, v66, v66
	v_add_f32_e32 v50, v61, v50
	v_add_f32_e32 v51, v72, v51
	v_add_f32_e32 v50, v63, v50
	v_add_f32_e32 v51, v73, v51
	v_add_f32_e32 v60, v50, v51
	ds_bpermute_b32 v61, v156, v60
	v_cvt_pk_bf16_f32 v50, v56, v57
	v_cvt_pk_bf16_f32 v51, v58, v59
	global_store_dwordx4 v[74:75], v[48:51], off
	s_waitcnt lgkmcnt(0)
	s_nop 0
	v_add_f32_e32 v48, v60, v61
	ds_bpermute_b32 v49, v155, v48
	v_cvt_pk_bf16_f32 v50, v52, v53
	v_cvt_pk_bf16_f32 v51, v54, v55
	v_cvt_pk_bf16_f32 v52, v68, v69
	v_cvt_pk_bf16_f32 v53, v66, v67
	global_store_dwordx4 v[74:75], v[50:53], off offset:256
	s_and_saveexec_b64 s[30:31], s[4:5]
	s_cbranch_execz .LBB0_797
	v_lshlrev_b64 v[50:51], 6, v[64:65]
	v_lshl_add_u64 v[50:51], s[12:13], 0, v[50:51]
	v_lshl_add_u64 v[50:51], s[28:29], 2, v[50:51]
	s_lshl_b32 s8, s49, 2
	v_lshl_add_u64 v[50:51], v[50:51], 0, s[8:9]
	s_waitcnt lgkmcnt(0)
	v_add_f32_e32 v48, v48, v49
	global_store_dword v[50:51], v48, off
.LBB0_797:
	s_or_b64 exec, exec, s[30:31]
	v_add_u32_e32 v48, 0x90, v146
	s_waitcnt lgkmcnt(0)
	v_ashrrev_i32_e32 v49, 31, v48
	v_lshlrev_b64 v[50:51], 11, v[48:49]
	v_lshl_add_u64 v[50:51], s[10:11], 0, v[50:51]
	v_lshl_add_u64 v[58:59], v[144:145], 1, v[50:51]
	s_waitcnt vmcnt(15)
	v_lshlrev_b32_e32 v60, 16, v208
	v_and_b32_e32 v61, 0xffff0000, v208
	v_lshlrev_b32_e32 v50, 16, v209
	v_and_b32_e32 v51, 0xffff0000, v209
	s_waitcnt vmcnt(14)
	v_lshlrev_b32_e32 v64, 16, v212
	v_and_b32_e32 v65, 0xffff0000, v212
	v_lshlrev_b32_e32 v54, 16, v213
	v_and_b32_e32 v55, 0xffff0000, v213
	v_lshlrev_b32_e32 v62, 16, v210
	v_and_b32_e32 v63, 0xffff0000, v210
	v_lshlrev_b32_e32 v52, 16, v211
	v_and_b32_e32 v53, 0xffff0000, v211
	v_lshlrev_b32_e32 v66, 16, v214
	v_and_b32_e32 v67, 0xffff0000, v214
	v_lshlrev_b32_e32 v56, 16, v215
	v_and_b32_e32 v57, 0xffff0000, v215
	v_pk_add_f32 v[46:47], v[46:47], v[50:51]
	v_pk_add_f32 v[44:45], v[44:45], v[60:61]
	v_pk_add_f32 v[38:39], v[38:39], v[54:55]
	v_pk_add_f32 v[36:37], v[36:37], v[64:65]
	v_pk_add_f32 v[42:43], v[42:43], v[52:53]
	v_pk_add_f32 v[40:41], v[40:41], v[62:63]
	v_pk_add_f32 v[50:51], v[34:35], v[56:57]
	v_pk_add_f32 v[52:53], v[32:33], v[66:67]
	v_mul_f32_e32 v34, v45, v45
	v_mul_f32_e32 v35, v47, v47
	v_mul_f32_e32 v54, v37, v37
	v_mul_f32_e32 v55, v39, v39
	v_cvt_pk_bf16_f32 v32, v44, v45
	v_mul_f32_e32 v45, v41, v41
	v_mul_f32_e32 v56, v53, v53
	v_fmac_f32_e32 v34, v44, v44
	v_fmac_f32_e32 v35, v46, v46
	v_fmac_f32_e32 v54, v36, v36
	v_fmac_f32_e32 v55, v38, v38
	v_cvt_pk_bf16_f32 v33, v46, v47
	v_mul_f32_e32 v47, v43, v43
	v_mul_f32_e32 v57, v51, v51
	v_fmac_f32_e32 v45, v40, v40
	v_fmac_f32_e32 v56, v52, v52
	v_add_f32_e32 v34, v34, v35
	v_add_f32_e32 v35, v54, v55
	v_fmac_f32_e32 v47, v42, v42
	v_fmac_f32_e32 v57, v50, v50
	v_add_f32_e32 v34, v45, v34
	v_add_f32_e32 v35, v56, v35
	v_add_f32_e32 v34, v47, v34
	v_add_f32_e32 v35, v57, v35
	v_add_f32_e32 v44, v34, v35
	ds_bpermute_b32 v45, v156, v44
	v_cvt_pk_bf16_f32 v34, v40, v41
	v_cvt_pk_bf16_f32 v35, v42, v43
	global_store_dwordx4 v[58:59], v[32:35], off
	s_waitcnt lgkmcnt(0)
	s_nop 0
	v_add_f32_e32 v32, v44, v45
	ds_bpermute_b32 v33, v155, v32
	v_cvt_pk_bf16_f32 v34, v36, v37
	v_cvt_pk_bf16_f32 v35, v38, v39
	v_cvt_pk_bf16_f32 v36, v52, v53
	v_cvt_pk_bf16_f32 v37, v50, v51
	global_store_dwordx4 v[58:59], v[34:37], off offset:256
	s_and_saveexec_b64 s[30:31], s[4:5]
	s_cbranch_execz .LBB0_799
	v_lshlrev_b64 v[34:35], 6, v[48:49]
	v_lshl_add_u64 v[34:35], s[12:13], 0, v[34:35]
	v_lshl_add_u64 v[34:35], s[28:29], 2, v[34:35]
	s_lshl_b32 s8, s49, 2
	v_lshl_add_u64 v[34:35], v[34:35], 0, s[8:9]
	s_waitcnt lgkmcnt(0)
	v_add_f32_e32 v32, v32, v33
	global_store_dword v[34:35], v32, off
.LBB0_799:
	s_or_b64 exec, exec, s[30:31]
	v_add_u32_e32 v32, 0xa0, v146
	s_waitcnt lgkmcnt(0)
	v_ashrrev_i32_e32 v33, 31, v32
	v_lshlrev_b64 v[34:35], 11, v[32:33]
	v_lshl_add_u64 v[34:35], s[10:11], 0, v[34:35]
	v_lshl_add_u64 v[42:43], v[144:145], 1, v[34:35]
	s_waitcnt vmcnt(15)
	v_lshlrev_b32_e32 v44, 16, v216
	v_and_b32_e32 v45, 0xffff0000, v216
	v_lshlrev_b32_e32 v34, 16, v217
	v_and_b32_e32 v35, 0xffff0000, v217
	s_waitcnt vmcnt(14)
	v_lshlrev_b32_e32 v48, 16, v220
	v_and_b32_e32 v49, 0xffff0000, v220
	v_lshlrev_b32_e32 v38, 16, v221
	v_and_b32_e32 v39, 0xffff0000, v221
	v_lshlrev_b32_e32 v46, 16, v218
	v_and_b32_e32 v47, 0xffff0000, v218
	v_lshlrev_b32_e32 v36, 16, v219
	v_and_b32_e32 v37, 0xffff0000, v219
	v_lshlrev_b32_e32 v50, 16, v222
	v_and_b32_e32 v51, 0xffff0000, v222
	v_lshlrev_b32_e32 v40, 16, v223
	v_and_b32_e32 v41, 0xffff0000, v223
	v_pk_add_f32 v[30:31], v[30:31], v[34:35]
	v_pk_add_f32 v[28:29], v[28:29], v[44:45]
	v_pk_add_f32 v[22:23], v[22:23], v[38:39]
	v_pk_add_f32 v[20:21], v[20:21], v[48:49]
	v_pk_add_f32 v[26:27], v[26:27], v[36:37]
	v_pk_add_f32 v[24:25], v[24:25], v[46:47]
	v_pk_add_f32 v[34:35], v[18:19], v[40:41]
	v_pk_add_f32 v[36:37], v[16:17], v[50:51]
	v_mul_f32_e32 v18, v29, v29
	v_mul_f32_e32 v19, v31, v31
	v_mul_f32_e32 v38, v21, v21
	v_mul_f32_e32 v39, v23, v23
	v_cvt_pk_bf16_f32 v16, v28, v29
	v_mul_f32_e32 v29, v25, v25
	v_mul_f32_e32 v40, v37, v37
	v_fmac_f32_e32 v18, v28, v28
	v_fmac_f32_e32 v19, v30, v30
	v_fmac_f32_e32 v38, v20, v20
	v_fmac_f32_e32 v39, v22, v22
	v_cvt_pk_bf16_f32 v17, v30, v31
	v_mul_f32_e32 v31, v27, v27
	v_mul_f32_e32 v41, v35, v35
	v_fmac_f32_e32 v29, v24, v24
	v_fmac_f32_e32 v40, v36, v36
	v_add_f32_e32 v18, v18, v19
	v_add_f32_e32 v19, v38, v39
	v_fmac_f32_e32 v31, v26, v26
	v_fmac_f32_e32 v41, v34, v34
	v_add_f32_e32 v18, v29, v18
	v_add_f32_e32 v19, v40, v19
	v_add_f32_e32 v18, v31, v18
	v_add_f32_e32 v19, v41, v19
	v_add_f32_e32 v28, v18, v19
	ds_bpermute_b32 v29, v156, v28
	v_cvt_pk_bf16_f32 v18, v24, v25
	v_cvt_pk_bf16_f32 v19, v26, v27
	global_store_dwordx4 v[42:43], v[16:19], off
	s_waitcnt lgkmcnt(0)
	s_nop 0
	v_add_f32_e32 v16, v28, v29
	ds_bpermute_b32 v17, v155, v16
	v_cvt_pk_bf16_f32 v18, v20, v21
	v_cvt_pk_bf16_f32 v19, v22, v23
	v_cvt_pk_bf16_f32 v20, v36, v37
	v_cvt_pk_bf16_f32 v21, v34, v35
	global_store_dwordx4 v[42:43], v[18:21], off offset:256
	s_and_saveexec_b64 s[30:31], s[4:5]
	s_cbranch_execz .LBB0_801
	v_lshlrev_b64 v[18:19], 6, v[32:33]
	v_lshl_add_u64 v[18:19], s[12:13], 0, v[18:19]
	v_lshl_add_u64 v[18:19], s[28:29], 2, v[18:19]
	s_lshl_b32 s8, s49, 2
	v_lshl_add_u64 v[18:19], v[18:19], 0, s[8:9]
	s_waitcnt lgkmcnt(0)
	v_add_f32_e32 v16, v16, v17
	global_store_dword v[18:19], v16, off
.LBB0_801:
	s_or_b64 exec, exec, s[30:31]
	v_add_u32_e32 v16, 0xb0, v146
	s_waitcnt lgkmcnt(0)
	v_ashrrev_i32_e32 v17, 31, v16
	v_lshlrev_b64 v[18:19], 11, v[16:17]
	v_lshl_add_u64 v[18:19], s[10:11], 0, v[18:19]
	v_lshl_add_u64 v[26:27], v[144:145], 1, v[18:19]
	s_waitcnt vmcnt(15)
	v_lshlrev_b32_e32 v28, 16, v224
	v_and_b32_e32 v29, 0xffff0000, v224
	v_lshlrev_b32_e32 v18, 16, v225
	v_and_b32_e32 v19, 0xffff0000, v225
	s_waitcnt vmcnt(14)
	v_lshlrev_b32_e32 v32, 16, v228
	v_and_b32_e32 v33, 0xffff0000, v228
	v_lshlrev_b32_e32 v22, 16, v229
	v_and_b32_e32 v23, 0xffff0000, v229
	v_lshlrev_b32_e32 v30, 16, v226
	v_and_b32_e32 v31, 0xffff0000, v226
	v_lshlrev_b32_e32 v20, 16, v227
	v_and_b32_e32 v21, 0xffff0000, v227
	v_lshlrev_b32_e32 v34, 16, v230
	v_and_b32_e32 v35, 0xffff0000, v230
	v_lshlrev_b32_e32 v24, 16, v231
	v_and_b32_e32 v25, 0xffff0000, v231
	v_pk_add_f32 v[14:15], v[14:15], v[18:19]
	v_pk_add_f32 v[12:13], v[12:13], v[28:29]
	v_pk_add_f32 v[6:7], v[6:7], v[22:23]
	v_pk_add_f32 v[4:5], v[4:5], v[32:33]
	v_pk_add_f32 v[10:11], v[10:11], v[20:21]
	v_pk_add_f32 v[8:9], v[8:9], v[30:31]
	v_pk_add_f32 v[18:19], v[2:3], v[24:25]
	v_pk_add_f32 v[20:21], v[0:1], v[34:35]
	v_mul_f32_e32 v2, v13, v13
	v_mul_f32_e32 v3, v15, v15
	v_mul_f32_e32 v22, v5, v5
	v_mul_f32_e32 v23, v7, v7
	v_cvt_pk_bf16_f32 v0, v12, v13
	v_mul_f32_e32 v13, v9, v9
	v_mul_f32_e32 v24, v21, v21
	v_fmac_f32_e32 v2, v12, v12
	v_fmac_f32_e32 v3, v14, v14
	v_fmac_f32_e32 v22, v4, v4
	v_fmac_f32_e32 v23, v6, v6
	v_cvt_pk_bf16_f32 v1, v14, v15
	v_mul_f32_e32 v15, v11, v11
	v_mul_f32_e32 v25, v19, v19
	v_fmac_f32_e32 v13, v8, v8
	v_fmac_f32_e32 v24, v20, v20
	v_add_f32_e32 v2, v2, v3
	v_add_f32_e32 v3, v22, v23
	v_fmac_f32_e32 v15, v10, v10
	v_fmac_f32_e32 v25, v18, v18
	v_add_f32_e32 v2, v13, v2
	v_add_f32_e32 v3, v24, v3
	v_add_f32_e32 v2, v15, v2
	v_add_f32_e32 v3, v25, v3
	v_add_f32_e32 v12, v2, v3
	ds_bpermute_b32 v13, v156, v12
	v_cvt_pk_bf16_f32 v2, v8, v9
	v_cvt_pk_bf16_f32 v3, v10, v11
	global_store_dwordx4 v[26:27], v[0:3], off
	s_waitcnt lgkmcnt(0)
	s_nop 0
	v_add_f32_e32 v0, v12, v13
	ds_bpermute_b32 v1, v155, v0
	v_cvt_pk_bf16_f32 v2, v4, v5
	v_cvt_pk_bf16_f32 v3, v6, v7
	v_cvt_pk_bf16_f32 v4, v20, v21
	v_cvt_pk_bf16_f32 v5, v18, v19
	global_store_dwordx4 v[26:27], v[2:5], off offset:256
	s_and_saveexec_b64 s[30:31], s[4:5]
	s_cbranch_execz .LBB0_782
	v_lshlrev_b64 v[2:3], 6, v[16:17]
	v_lshl_add_u64 v[2:3], s[12:13], 0, v[2:3]
	v_lshl_add_u64 v[2:3], s[28:29], 2, v[2:3]
	s_lshl_b32 s8, s49, 2
	v_lshl_add_u64 v[2:3], v[2:3], 0, s[8:9]
	s_waitcnt lgkmcnt(0)
	v_add_f32_e32 v0, v0, v1
	global_store_dword v[2:3], v0, off
	s_branch .LBB0_782

	.amdhsa_kernel _Z9hymba_fwd6Params
		.amdhsa_group_segment_fixed_size 0
		.amdhsa_private_segment_fixed_size 0
		.amdhsa_kernarg_size 432
		.amdhsa_user_sgpr_count 2
		.amdhsa_user_sgpr_dispatch_ptr 0
		.amdhsa_user_sgpr_queue_ptr 0
		.amdhsa_user_sgpr_kernarg_segment_ptr 1
		.amdhsa_user_sgpr_dispatch_id 0
		.amdhsa_user_sgpr_kernarg_preload_length 0
		.amdhsa_user_sgpr_kernarg_preload_offset 0
		.amdhsa_user_sgpr_private_segment_size 0
		.amdhsa_uses_dynamic_stack 0
		.amdhsa_enable_private_segment 0
		.amdhsa_system_sgpr_workgroup_id_x 1
		.amdhsa_system_sgpr_workgroup_id_y 0
		.amdhsa_system_sgpr_workgroup_id_z 0
		.amdhsa_system_sgpr_workgroup_info 0
		.amdhsa_system_vgpr_workitem_id 2
		.amdhsa_next_free_vgpr 248
		.amdhsa_next_free_sgpr 88
		.amdhsa_accum_offset 248
		.amdhsa_reserve_vcc 1
		.amdhsa_float_round_mode_32 0
		.amdhsa_float_round_mode_16_64 0
		.amdhsa_float_denorm_mode_32 3
		.amdhsa_float_denorm_mode_16_64 3
		.amdhsa_dx10_clamp 1
		.amdhsa_ieee_mode 1
		.amdhsa_fp16_overflow 0
		.amdhsa_tg_split 0
		.amdhsa_exception_fp_ieee_invalid_op 0
		.amdhsa_exception_fp_denorm_src 0
		.amdhsa_exception_fp_ieee_div_zero 0
		.amdhsa_exception_fp_ieee_overflow 0
		.amdhsa_exception_fp_ieee_underflow 0
		.amdhsa_exception_fp_ieee_inexact 0
		.amdhsa_exception_int_div_zero 0
	.end_amdhsa_kernel

amdhsa.kernels:
  - .agpr_count:     0
    .args:
      - .offset:         0
        .size:           176
        .value_kind:     by_value
      - .offset:         176
        .size:           4
        .value_kind:     hidden_block_count_x
      - .offset:         180
        .size:           4
        .value_kind:     hidden_block_count_y
      - .offset:         184
        .size:           4
        .value_kind:     hidden_block_count_z
      - .offset:         188
        .size:           2
        .value_kind:     hidden_group_size_x
      - .offset:         190
        .size:           2
        .value_kind:     hidden_group_size_y
      - .offset:         192
        .size:           2
        .value_kind:     hidden_group_size_z
      - .offset:         194
        .size:           2
        .value_kind:     hidden_remainder_x
      - .offset:         196
        .size:           2
        .value_kind:     hidden_remainder_y
      - .offset:         198
        .size:           2
        .value_kind:     hidden_remainder_z
      - .offset:         216
        .size:           8
        .value_kind:     hidden_global_offset_x
      - .offset:         224
        .size:           8
        .value_kind:     hidden_global_offset_y
      - .offset:         232
        .size:           8
        .value_kind:     hidden_global_offset_z
      - .offset:         240
        .size:           2
        .value_kind:     hidden_grid_dims
      - .offset:         264
        .size:           8
        .value_kind:     hidden_multigrid_sync_arg
      - .offset:         296
        .size:           4
        .value_kind:     hidden_dynamic_lds_size
    .group_segment_fixed_size: 0
    .kernarg_segment_align: 8
    .kernarg_segment_size: 432
    .language:       OpenCL C
    .language_version:
      - 2
      - 0
    .max_flat_workgroup_size: 512
    .name:           _Z9hymba_fwd6Params
    .private_segment_fixed_size: 0
    .sgpr_count:     94
    .sgpr_spill_count: 0
    .symbol:         _Z9hymba_fwd6Params.kd
    .uniform_work_group_size: 1
    .uses_dynamic_stack: false
    .vgpr_count:     248
    .vgpr_spill_count: 0
    .wavefront_size: 64
